# Fourier layers: sequence-FFT output Y stored chunk-major ([K/8][tokens][8]) so the FFT phase writes contiguously; out-projection A operand addressed accordingly
# speedup vs baseline: 1.0065x; 1.0042x over previous
; __device__ __forceinline__ unsigned cvt_pk_bf16(float lo, float hi) { f32x2_t v = {lo, hi}; bf16x2_t b = __builtin_convertvector(v, bf16x2_t); return __builtin_bit_cast(unsigned, b); }
; #define LAS __attribute__((address_space(3)))
; template <int N, int LOGN> __device__ __forceinline__ void fft_dif(float (&re)[N], float (&im)[N]) {
; #pragma unroll
;     for (int st = 0; st < LOGN; ++st) { const int len = N >> st, half = len >> 1, step = 32 / len;
; #pragma unroll
;         for (int base = 0; base < N; base += len)
; #pragma unroll
;             for (int j = 0; j < half; ++j) { const int a = base + j, b = a + half;
;                 const float ar = re[a], ai = im[a], br = re[b], bi = im[b]; re[a] = ar + br; im[a] = ai + bi;
;                 const float dr = ar - br, di = ai - bi; const int m = (j * step) & 31;
;                 if (m == 0) { re[b] = dr; im[b] = di; }
;                 else if (m == 8) { re[b] = di; im[b] = -dr; }
;                 else { const float wr = C32[m], ws = C32[(m + 24) & 31]; re[b] = dr * wr + di * ws; im[b] = di * wr - dr * ws; }
;                 asm("" : "+v"(re[a])); asm("" : "+v"(im[a])); asm("" : "+v"(re[b])); asm("" : "+v"(im[b])); } }
; __device__ __forceinline__ void fft_phase(Frame& F, const bf16* Yc, bf16* Y) {
;     ...
;         { const int col = t >> 1; LAS unsigned char* l3 = buf + 16 * (529 * (col >> 4) + 33 * (col & 15)) + 8 * (t & 1);
; #pragma unroll 1
;           for (int c = 0; c < 2; ++c) { float re[32], im[32];
; #pragma unroll
;               for (int qq = 0; qq < 32; ++qq) { const unsigned w = *(const LAS unsigned*)(l3 + 4 * c + 16 * qq); re[qq] = bflo(w); im[qq] = bfhi(w); }
;               fft_dif<32, 5>(re, im);
; #pragma unroll
;               for (int k = 0; k < 32; ++k) *(LAS unsigned*)(l3 + 4 * c + 16 * k) = pg8::cvt_pk_bf16(re[BR5[k]], im[BR5[k]]); } }
.LBB0_201:
	v_cndmask_b32_e64 v2, 0, 1, s[4:5]
	v_add_u32_e32 v11, s0, v195
	v_cmp_ne_u32_e32 vcc, 1, v2
	ds_read2_b32 v[2:3], v11 offset1:4
	ds_read2_b32 v[4:5], v11 offset0:8 offset1:12
	ds_read2_b32 v[6:7], v11 offset0:16 offset1:20
	ds_read2_b32 v[8:9], v11 offset0:24 offset1:28
	ds_read2_b32 v[138:139], v11 offset0:32 offset1:36
	ds_read2_b32 v[140:141], v11 offset0:40 offset1:44
	ds_read2_b32 v[162:163], v11 offset0:48 offset1:52
	ds_read2_b32 v[168:169], v11 offset0:56 offset1:60
	ds_read2_b32 v[142:143], v11 offset0:64 offset1:68
	s_waitcnt lgkmcnt(8)
	v_lshlrev_b32_e32 v198, 16, v2
	v_and_b32_e32 v209, 0xffff0000, v2
	v_lshlrev_b32_e32 v205, 16, v3
	v_and_b32_e32 v204, 0xffff0000, v3
	ds_read2_b32 v[2:3], v11 offset0:72 offset1:76
	s_waitcnt lgkmcnt(1)
	v_lshlrev_b32_e32 v208, 16, v142
	v_and_b32_e32 v199, 0xffff0000, v142
	v_lshlrev_b32_e32 v171, 16, v143
	v_and_b32_e32 v170, 0xffff0000, v143
	s_waitcnt lgkmcnt(0)
	v_lshlrev_b32_e32 v155, 16, v2
	v_and_b32_e32 v154, 0xffff0000, v2
	v_lshlrev_b32_e32 v161, 16, v3
	v_and_b32_e32 v160, 0xffff0000, v3
	ds_read2_b32 v[2:3], v11 offset0:80 offset1:84
	v_lshlrev_b32_e32 v177, 16, v4
	v_and_b32_e32 v176, 0xffff0000, v4
	v_lshlrev_b32_e32 v149, 16, v162
	v_and_b32_e32 v148, 0xffff0000, v162
	s_waitcnt lgkmcnt(0)
	v_lshlrev_b32_e32 v181, 16, v2
	v_and_b32_e32 v180, 0xffff0000, v2
	v_lshlrev_b32_e32 v173, 16, v3
	v_and_b32_e32 v172, 0xffff0000, v3
	ds_read2_b32 v[2:3], v11 offset0:88 offset1:92
	v_lshlrev_b32_e32 v145, 16, v163
	v_and_b32_e32 v144, 0xffff0000, v163
	v_pk_add_f32 v[162:163], v[204:205], v[170:171] neg_lo:[0,1] neg_hi:[0,1]
	s_mov_b32 s6, s71
	s_waitcnt lgkmcnt(0)
	v_lshlrev_b32_e32 v165, 16, v2
	v_and_b32_e32 v164, 0xffff0000, v2
	v_lshlrev_b32_e32 v175, 16, v3
	v_and_b32_e32 v174, 0xffff0000, v3
	ds_read2_b32 v[2:3], v11 offset0:96 offset1:100
	s_mov_b32 s7, s70
	v_lshlrev_b32_e32 v191, 16, v6
	v_and_b32_e32 v190, 0xffff0000, v6
	v_lshlrev_b32_e32 v179, 16, v7
	s_waitcnt lgkmcnt(0)
	v_lshlrev_b32_e32 v206, 16, v2
	v_and_b32_e32 v202, 0xffff0000, v2
	v_lshlrev_b32_e32 v185, 16, v3
	v_and_b32_e32 v184, 0xffff0000, v3
	ds_read2_b32 v[2:3], v11 offset0:104 offset1:108
	v_and_b32_e32 v178, 0xffff0000, v7
	v_lshlrev_b32_e32 v183, 16, v8
	v_and_b32_e32 v182, 0xffff0000, v8
	v_lshlrev_b32_e32 v187, 16, v9
	s_waitcnt lgkmcnt(0)
	v_lshlrev_b32_e32 v157, 16, v2
	v_and_b32_e32 v156, 0xffff0000, v2
	v_lshlrev_b32_e32 v151, 16, v3
	v_and_b32_e32 v150, 0xffff0000, v3
	ds_read2_b32 v[2:3], v11 offset0:112 offset1:116
	v_and_b32_e32 v186, 0xffff0000, v9
	v_lshlrev_b32_e32 v203, 16, v138
	v_and_b32_e32 v207, 0xffff0000, v138
	v_lshlrev_b32_e32 v189, 16, v139
	s_waitcnt lgkmcnt(0)
	v_lshlrev_b32_e32 v147, 16, v2
	v_and_b32_e32 v146, 0xffff0000, v2
	v_lshlrev_b32_e32 v143, 16, v3
	v_and_b32_e32 v142, 0xffff0000, v3
	ds_read2_b32 v[2:3], v11 offset0:120 offset1:124
	v_and_b32_e32 v188, 0xffff0000, v139
	v_lshlrev_b32_e32 v159, 16, v140
	v_and_b32_e32 v158, 0xffff0000, v140
	v_lshlrev_b32_e32 v153, 16, v141
	v_and_b32_e32 v152, 0xffff0000, v141
	s_waitcnt lgkmcnt(0)
	v_lshlrev_b32_e32 v139, 16, v2
	v_lshlrev_b32_e32 v141, 16, v168
	v_and_b32_e32 v138, 0xffff0000, v2
	v_and_b32_e32 v140, 0xffff0000, v168
	v_lshlrev_b32_e32 v7, 16, v3
	v_lshlrev_b32_e32 v9, 16, v169
	v_and_b32_e32 v6, 0xffff0000, v3
	v_and_b32_e32 v8, 0xffff0000, v169
	v_pk_mul_f32 v[2:3], v[162:163], s[70:71]
	v_pk_mul_f32 v[162:163], v[162:163], s[6:7]
	v_pk_add_f32 v[168:169], v[176:177], v[154:155] neg_lo:[0,1] neg_hi:[0,1]
	s_mov_b32 s31, s66
	s_mov_b32 s67, s30
	v_lshlrev_b32_e32 v193, 16, v5
	v_and_b32_e32 v192, 0xffff0000, v5
	v_add_f32_e32 v3, v3, v2
	v_sub_f32_e32 v2, v162, v163
	v_add_f32_e32 v163, v155, v177
	v_add_f32_e32 v162, v154, v176
	v_pk_mul_f32 v[154:155], v[168:169], s[30:31]
	v_pk_mul_f32 v[168:169], v[168:169], s[66:67]
	v_add_f32_e32 v155, v155, v154
	v_sub_f32_e32 v154, v168, v169
	v_pk_add_f32 v[168:169], v[192:193], v[160:161] neg_lo:[0,1] neg_hi:[0,1]
	s_mov_b32 s4, s29
	s_mov_b32 s5, s28
	v_add_f32_e32 v177, v161, v193
	v_add_f32_e32 v176, v160, v192
	v_pk_mul_f32 v[160:161], v[168:169], s[28:29]
	v_pk_mul_f32 v[168:169], v[168:169], s[4:5]
	v_add_f32_e32 v161, v161, v160
	v_sub_f32_e32 v160, v168, v169
	v_pk_add_f32 v[168:169], v[190:191], v[180:181] neg_lo:[0,1] neg_hi:[0,1]
	v_add_f32_e32 v192, v181, v191
	v_pk_mul_f32 v[168:169], v[168:169], s[36:37] op_sel_hi:[1,0]
	v_add_f32_e32 v193, v180, v190
	v_add_f32_e32 v190, v169, v168
	v_sub_f32_e32 v191, v168, v169
	v_pk_add_f32 v[168:169], v[178:179], v[172:173] neg_lo:[0,1] neg_hi:[0,1]
	v_add_f32_e32 v5, v171, v205
	v_add_f32_e32 v4, v170, v204
	v_pk_mul_f32 v[170:171], v[168:169], s[4:5]
	v_pk_mul_f32 v[168:169], v[168:169], s[28:29]
	v_add_f32_e32 v180, v172, v178
	v_sub_f32_e32 v172, v168, v169
	v_pk_add_f32 v[168:169], v[182:183], v[164:165] neg_lo:[0,1] neg_hi:[0,1]
	v_add_f32_e32 v181, v173, v179
	v_add_f32_e32 v179, v165, v183
	v_add_f32_e32 v178, v164, v182
	v_pk_mul_f32 v[164:165], v[168:169], s[66:67]
	v_pk_mul_f32 v[168:169], v[168:169], s[30:31]
	v_add_f32_e32 v165, v165, v164
	v_sub_f32_e32 v164, v168, v169
	v_pk_add_f32 v[168:169], v[186:187], v[174:175] neg_lo:[0,1] neg_hi:[0,1]
	v_add_f32_e32 v173, v171, v170
	v_pk_mul_f32 v[170:171], v[168:169], s[6:7]
	v_pk_mul_f32 v[168:169], v[168:169], s[70:71]
	v_add_f32_e32 v183, v175, v187
	v_add_f32_e32 v182, v174, v186
	v_sub_f32_e32 v174, v168, v169
	v_sub_f32_e32 v168, v203, v206
	v_add_f32_e32 v187, v185, v189
	v_add_f32_e32 v186, v184, v188
	v_pk_add_f32 v[188:189], v[188:189], v[184:185] neg_lo:[0,1] neg_hi:[0,1]
	v_add_f32_e32 v204, v206, v203
	v_xor_b32_e32 v203, 0x80000000, v168
; template <int N, int LOGN> __device__ __forceinline__ void fft_dif(float (&re)[N], float (&im)[N]) {
; #pragma unroll
;     for (int st = 0; st < LOGN; ++st) { const int len = N >> st, half = len >> 1, step = 32 / len;
; #pragma unroll
;         for (int base = 0; base < N; base += len)
; #pragma unroll
;             for (int j = 0; j < half; ++j) { const int a = base + j, b = a + half;
;                 const float ar = re[a], ai = im[a], br = re[b], bi = im[b]; re[a] = ar + br; im[a] = ai + bi;
;                 const float dr = ar - br, di = ai - bi; const int m = (j * step) & 31;
;                 if (m == 0) { re[b] = dr; im[b] = di; }
;                 else if (m == 8) { re[b] = di; im[b] = -dr; }
;                 else { const float wr = C32[m], ws = C32[(m + 24) & 31]; re[b] = dr * wr + di * ws; im[b] = di * wr - dr * ws; }
;                 asm("" : "+v"(re[a])); asm("" : "+v"(im[a])); asm("" : "+v"(re[b])); asm("" : "+v"(im[b])); } }
	v_pk_mul_f32 v[168:169], v[188:189], s[6:7]
	s_mov_b32 s49, s71
	v_sub_f32_e32 v185, v168, v169
	v_pk_mul_f32 v[168:169], v[188:189], s[48:49]
	s_mov_b32 s27, s36
	v_sub_f32_e32 v184, v168, v169
	v_add_f32_e32 v168, v147, v149
	v_add_f32_e32 v169, v146, v148
	v_pk_add_f32 v[146:147], v[148:149], v[146:147] neg_lo:[0,1] neg_hi:[0,1]
	v_add_f32_e32 v175, v171, v170
	v_pk_mul_f32 v[148:149], v[146:147], s[26:27]
	v_add_f32_e32 v147, v143, v145
	v_fma_f32 v170, v146, s36, -v149
	v_add_f32_e32 v146, v142, v144
	v_pk_add_f32 v[144:145], v[144:145], v[142:143] neg_lo:[0,1] neg_hi:[0,1]
	s_mov_b32 s53, s28
	v_pk_mul_f32 v[142:143], v[144:145], s[28:29]
	v_pk_mul_f32 v[144:145], v[144:145], s[52:53]
	v_sub_f32_e32 v143, v142, v143
	v_sub_f32_e32 v142, v144, v145
	v_add_f32_e32 v145, v139, v141
	v_add_f32_e32 v144, v138, v140
	v_pk_add_f32 v[140:141], v[140:141], v[138:139] neg_lo:[0,1] neg_hi:[0,1]
	s_mov_b32 s47, s30
	v_pk_mul_f32 v[138:139], v[140:141], s[30:31]
	v_pk_mul_f32 v[140:141], v[140:141], s[46:47]
	v_sub_f32_e32 v139, v138, v139
	v_sub_f32_e32 v138, v140, v141
	v_add_f32_e32 v141, v7, v9
	v_add_f32_e32 v140, v6, v8
	v_pk_add_f32 v[6:7], v[8:9], v[6:7] neg_lo:[0,1] neg_hi:[0,1]
	s_mov_b32 s55, s70
	v_add_f32_e32 v189, v157, v159
	v_add_f32_e32 v188, v156, v158
	v_pk_add_f32 v[158:159], v[158:159], v[156:157] neg_lo:[0,1] neg_hi:[0,1]
	s_mov_b32 s69, s66
	v_pk_mul_f32 v[8:9], v[6:7], s[70:71]
	v_pk_mul_f32 v[6:7], v[6:7], s[54:55]
	v_pk_mul_f32 v[156:157], v[158:159], s[66:67]
	v_pk_mul_f32 v[158:159], v[158:159], s[68:69]
	v_sub_f32_e32 v9, v8, v9
	v_sub_f32_e32 v8, v6, v7
	v_add_f32_e32 v7, v5, v187
	v_add_f32_e32 v6, v4, v186
	v_pk_add_f32 v[4:5], v[4:5], v[186:187] neg_lo:[0,1] neg_hi:[0,1]
	v_sub_f32_e32 v157, v156, v157
	v_sub_f32_e32 v156, v158, v159
	v_add_f32_e32 v159, v151, v153
	v_add_f32_e32 v158, v150, v152
	v_pk_add_f32 v[152:153], v[152:153], v[150:151] neg_lo:[0,1] neg_hi:[0,1]
	s_mov_b32 s51, s29
	v_sub_f32_e32 v171, v148, v149
	v_pk_mul_f32 v[148:149], v[4:5], s[30:31]
	v_pk_mul_f32 v[4:5], v[4:5], s[66:67]
	v_pk_mul_f32 v[150:151], v[152:153], s[4:5]
	v_pk_mul_f32 v[152:153], v[152:153], s[50:51]
	v_add_f32_e32 v149, v149, v148
	v_sub_f32_e32 v148, v4, v5
	v_pk_add_f32 v[4:5], v[162:163], v[188:189] neg_lo:[0,1] neg_hi:[0,1]
	v_sub_f32_e32 v151, v150, v151
	v_sub_f32_e32 v150, v152, v153
	v_pk_mul_f32 v[4:5], v[4:5], s[36:37] op_sel_hi:[1,0]
	v_pk_add_f32 v[152:153], v[176:177], v[158:159] neg_lo:[0,1] neg_hi:[0,1]
	v_add_f32_e32 v186, v163, v189
	v_add_f32_e32 v187, v162, v188
	v_add_f32_e32 v188, v5, v4
	v_sub_f32_e32 v189, v4, v5
	v_add_f32_e32 v5, v177, v159
	v_add_f32_e32 v4, v176, v158
	v_pk_mul_f32 v[158:159], v[152:153], s[66:67]
	v_pk_mul_f32 v[152:153], v[152:153], s[30:31]
	v_add_f32_e32 v159, v159, v158
	v_sub_f32_e32 v158, v152, v153
	v_sub_f32_e32 v152, v192, v168
	v_add_f32_e32 v176, v192, v168
	v_xor_b32_e32 v192, 0x80000000, v152
	v_add_f32_e32 v153, v181, v147
	v_add_f32_e32 v152, v180, v146
	v_pk_add_f32 v[146:147], v[180:181], v[146:147] neg_lo:[0,1] neg_hi:[0,1]
	s_nop 0
	v_pk_mul_f32 v[162:163], v[146:147], s[66:67]
	v_pk_mul_f32 v[146:147], v[146:147], s[68:69]
	v_add_f32_e32 v180, v179, v145
	v_add_f32_e32 v181, v178, v144
	v_pk_add_f32 v[144:145], v[178:179], v[144:145] neg_lo:[0,1] neg_hi:[0,1]
	v_sub_f32_e32 v163, v162, v163
	v_sub_f32_e32 v162, v146, v147
	v_pk_mul_f32 v[146:147], v[144:145], s[26:27]
	v_add_f32_e32 v145, v183, v141
	v_fma_f32 v178, v144, s36, -v147
	v_add_f32_e32 v144, v182, v140
	v_pk_add_f32 v[140:141], v[182:183], v[140:141] neg_lo:[0,1] neg_hi:[0,1]
	v_sub_f32_e32 v179, v146, v147
	v_pk_mul_f32 v[146:147], v[140:141], s[30:31]
	v_pk_mul_f32 v[140:141], v[140:141], s[46:47]
	v_sub_f32_e32 v147, v146, v147
	v_sub_f32_e32 v146, v140, v141
	v_add_f32_e32 v141, v3, v185
	v_add_f32_e32 v140, v2, v184
	v_pk_add_f32 v[2:3], v[2:3], v[184:185] neg_lo:[0,1] neg_hi:[0,1]
	v_add_f32_e32 v177, v193, v169
	v_sub_f32_e32 v193, v193, v169
	v_pk_mul_f32 v[168:169], v[2:3], s[30:31]
	v_pk_mul_f32 v[2:3], v[2:3], s[66:67]
	v_add_f32_e32 v200, v208, v198
	v_add_f32_e32 v201, v199, v209
	v_sub_f32_e32 v199, v209, v199
	v_sub_f32_e32 v198, v198, v208
	v_add_f32_e32 v205, v202, v207
	v_sub_f32_e32 v202, v207, v202
	v_add_f32_e32 v169, v169, v168
	v_sub_f32_e32 v168, v2, v3
	v_pk_add_f32 v[2:3], v[154:155], v[156:157] neg_lo:[0,1] neg_hi:[0,1]
	s_nop 0
	v_pk_mul_f32 v[2:3], v[2:3], s[36:37] op_sel_hi:[1,0]
	v_add_f32_e32 v182, v198, v202
	v_add_f32_e32 v183, v199, v203
	v_sub_f32_e32 v199, v199, v203
	v_sub_f32_e32 v198, v198, v202
	v_add_f32_e32 v202, v3, v2
	v_sub_f32_e32 v203, v2, v3
	v_add_f32_e32 v3, v161, v151
	v_add_f32_e32 v2, v160, v150
	v_pk_add_f32 v[150:151], v[160:161], v[150:151] neg_lo:[0,1] neg_hi:[0,1]
	v_add_f32_e32 v184, v155, v157
	v_add_f32_e32 v185, v154, v156
	v_pk_mul_f32 v[154:155], v[150:151], s[66:67]
	v_pk_mul_f32 v[150:151], v[150:151], s[30:31]
	v_add_f32_e32 v155, v155, v154
	v_sub_f32_e32 v154, v150, v151
	v_sub_f32_e32 v150, v190, v170
	v_add_f32_e32 v160, v190, v170
	v_xor_b32_e32 v170, 0x80000000, v150
	v_add_f32_e32 v151, v173, v143
	v_add_f32_e32 v150, v172, v142
	v_pk_add_f32 v[142:143], v[172:173], v[142:143] neg_lo:[0,1] neg_hi:[0,1]
	s_nop 0
	v_pk_mul_f32 v[156:157], v[142:143], s[66:67]
	v_pk_mul_f32 v[142:143], v[142:143], s[68:69]
	v_add_f32_e32 v172, v165, v139
	v_add_f32_e32 v173, v164, v138
	v_pk_add_f32 v[138:139], v[164:165], v[138:139] neg_lo:[0,1] neg_hi:[0,1]
	v_sub_f32_e32 v157, v156, v157
	v_sub_f32_e32 v156, v142, v143
	v_pk_mul_f32 v[142:143], v[138:139], s[26:27]
	v_add_f32_e32 v139, v175, v9
	v_fma_f32 v164, v138, s36, -v143
; template <int N, int LOGN> __device__ __forceinline__ void fft_dif(float (&re)[N], float (&im)[N]) {
; #pragma unroll
;     for (int st = 0; st < LOGN; ++st) { const int len = N >> st, half = len >> 1, step = 32 / len;
; #pragma unroll
;         for (int base = 0; base < N; base += len)
; #pragma unroll
;             for (int j = 0; j < half; ++j) { const int a = base + j, b = a + half;
;                 const float ar = re[a], ai = im[a], br = re[b], bi = im[b]; re[a] = ar + br; im[a] = ai + bi;
;                 const float dr = ar - br, di = ai - bi; const int m = (j * step) & 31;
;                 if (m == 0) { re[b] = dr; im[b] = di; }
;                 else if (m == 8) { re[b] = di; im[b] = -dr; }
;                 else { const float wr = C32[m], ws = C32[(m + 24) & 31]; re[b] = dr * wr + di * ws; im[b] = di * wr - dr * ws; }
;                 asm("" : "+v"(re[a])); asm("" : "+v"(im[a])); asm("" : "+v"(re[b])); asm("" : "+v"(im[b])); } }
	v_add_f32_e32 v138, v174, v8
	v_pk_add_f32 v[8:9], v[174:175], v[8:9] neg_lo:[0,1] neg_hi:[0,1]
	s_nop 0
	v_add_f32_e32 v206, v200, v204
	v_add_f32_e32 v207, v201, v205
	v_sub_f32_e32 v165, v142, v143
	v_pk_mul_f32 v[142:143], v[8:9], s[30:31]
	v_pk_mul_f32 v[8:9], v[8:9], s[46:47]
	v_sub_f32_e32 v143, v142, v143
	v_sub_f32_e32 v142, v8, v9
	v_add_f32_e32 v8, v206, v176
	v_add_f32_e32 v9, v207, v177
	v_sub_f32_e32 v174, v207, v177
	v_sub_f32_e32 v175, v206, v176
	v_add_f32_e32 v176, v7, v153
	v_add_f32_e32 v177, v6, v152
	v_pk_add_f32 v[6:7], v[6:7], v[152:153] neg_lo:[0,1] neg_hi:[0,1]
	s_nop 0
	v_pk_mul_f32 v[6:7], v[6:7], s[36:37] op_sel_hi:[1,0]
	v_add_f32_e32 v161, v191, v171
	v_sub_f32_e32 v171, v191, v171
	v_add_f32_e32 v152, v7, v6
	v_sub_f32_e32 v153, v6, v7
	v_add_f32_e32 v190, v186, v180
	v_add_f32_e32 v191, v187, v181
	v_sub_f32_e32 v181, v187, v181
	v_sub_f32_e32 v6, v186, v180
	v_add_f32_e32 v186, v5, v145
	v_add_f32_e32 v187, v4, v144
	v_pk_add_f32 v[4:5], v[4:5], v[144:145] neg_lo:[0,1] neg_hi:[0,1]
	v_xor_b32_e32 v180, 0x80000000, v6
	v_pk_mul_f32 v[6:7], v[4:5], s[26:27]
	v_sub_f32_e32 v201, v201, v205
	v_sub_f32_e32 v200, v200, v204
	v_fma_f32 v144, v4, s36, -v7
	v_pk_add_f32 v[4:5], v[148:149], v[162:163] neg_lo:[0,1] neg_hi:[0,1]
	s_nop 0
	v_pk_mul_f32 v[4:5], v[4:5], s[36:37] op_sel_hi:[1,0]
	v_add_f32_e32 v204, v200, v193
	v_add_f32_e32 v205, v201, v192
	v_sub_f32_e32 v192, v201, v192
	v_sub_f32_e32 v193, v200, v193
	v_add_f32_e32 v200, v149, v163
	v_add_f32_e32 v201, v148, v162
	v_add_f32_e32 v148, v5, v4
	v_sub_f32_e32 v149, v4, v5
	v_sub_f32_e32 v4, v188, v178
	v_add_f32_e32 v162, v188, v178
	v_xor_b32_e32 v178, 0x80000000, v4
	v_pk_add_f32 v[4:5], v[158:159], v[146:147] neg_lo:[0,1] neg_hi:[0,1]
	v_sub_f32_e32 v145, v6, v7
	v_pk_mul_f32 v[6:7], v[4:5], s[26:27]
	v_add_f32_e32 v163, v189, v179
	v_sub_f32_e32 v179, v189, v179
	v_add_f32_e32 v189, v158, v146
	v_fma_f32 v146, v4, s36, -v7
	v_pk_add_f32 v[4:5], v[140:141], v[150:151] neg_lo:[0,1] neg_hi:[0,1]
	s_nop 0
	v_pk_mul_f32 v[4:5], v[4:5], s[36:37] op_sel_hi:[1,0]
	v_add_f32_e32 v188, v159, v147
	v_sub_f32_e32 v6, v6, v7
	v_add_f32_e32 v7, v182, v160
	v_add_f32_e32 v147, v183, v161
	v_sub_f32_e32 v158, v183, v161
	v_sub_f32_e32 v159, v182, v160
	v_add_f32_e32 v160, v141, v151
	v_add_f32_e32 v161, v140, v150
	v_add_f32_e32 v140, v5, v4
	v_sub_f32_e32 v141, v4, v5
	v_sub_f32_e32 v4, v184, v172
	v_add_f32_e32 v182, v3, v139
	v_add_f32_e32 v183, v2, v138
	v_pk_add_f32 v[2:3], v[2:3], v[138:139] neg_lo:[0,1] neg_hi:[0,1]
	v_add_f32_e32 v150, v184, v172
	v_xor_b32_e32 v172, 0x80000000, v4
	v_pk_mul_f32 v[4:5], v[2:3], s[26:27]
	s_nop 0
	v_fma_f32 v138, v2, s36, -v5
	v_pk_add_f32 v[2:3], v[168:169], v[156:157] neg_lo:[0,1] neg_hi:[0,1]
	s_nop 0
	v_pk_mul_f32 v[2:3], v[2:3], s[36:37] op_sel_hi:[1,0]
	v_add_f32_e32 v151, v185, v173
	v_sub_f32_e32 v173, v185, v173
	v_add_f32_e32 v184, v198, v171
	v_add_f32_e32 v185, v199, v170
	v_sub_f32_e32 v170, v199, v170
	v_sub_f32_e32 v171, v198, v171
	v_add_f32_e32 v198, v169, v157
	v_add_f32_e32 v199, v168, v156
	v_add_f32_e32 v156, v3, v2
	v_sub_f32_e32 v157, v2, v3
	v_sub_f32_e32 v2, v202, v164
	v_add_f32_e32 v168, v202, v164
	v_xor_b32_e32 v164, 0x80000000, v2
	v_pk_add_f32 v[2:3], v[154:155], v[142:143] neg_lo:[0,1] neg_hi:[0,1]
	v_sub_f32_e32 v139, v4, v5
	v_pk_mul_f32 v[4:5], v[2:3], s[26:27]
	v_add_f32_e32 v169, v203, v165
	v_sub_f32_e32 v165, v203, v165
	v_add_f32_e32 v202, v155, v143
	v_add_f32_e32 v203, v154, v142
	v_fma_f32 v2, v2, s36, -v5
	v_sub_f32_e32 v3, v4, v5
	v_add_f32_e32 v4, v8, v190
	v_add_f32_e32 v5, v9, v191
	v_sub_f32_e32 v9, v9, v191
	v_add_f32_e32 v142, v176, v186
	v_add_f32_e32 v143, v177, v187
	v_sub_f32_e32 v154, v177, v187
	v_sub_f32_e32 v155, v176, v186
	v_add_f32_e32 v177, v174, v180
	v_sub_f32_e32 v174, v174, v180
	v_add_f32_e32 v180, v152, v144
	v_sub_f32_e32 v144, v152, v144
	v_add_f32_e32 v186, v200, v188
	v_sub_f32_e32 v188, v200, v188
	v_add_f32_e32 v191, v192, v178
	v_sub_f32_e32 v178, v192, v178
	v_add_f32_e32 v192, v148, v146
	v_sub_f32_e32 v146, v148, v146
	v_sub_f32_e32 v8, v8, v190
	v_xor_b32_e32 v155, 0x80000000, v155
	v_add_f32_e32 v176, v175, v181
	v_sub_f32_e32 v175, v175, v181
	v_add_f32_e32 v181, v153, v145
	v_sub_f32_e32 v145, v153, v145
	v_xor_b32_e32 v144, 0x80000000, v144
	v_add_f32_e32 v152, v204, v162
	v_add_f32_e32 v153, v205, v163
	v_sub_f32_e32 v163, v205, v163
	v_sub_f32_e32 v162, v204, v162
	v_add_f32_e32 v187, v201, v189
	v_sub_f32_e32 v189, v201, v189
	v_xor_b32_e32 v188, 0x80000000, v188
	v_add_f32_e32 v190, v193, v179
	v_sub_f32_e32 v179, v193, v179
	v_add_f32_e32 v193, v149, v6
	v_sub_f32_e32 v6, v149, v6
	v_xor_b32_e32 v146, 0x80000000, v146
	v_add_f32_e32 v148, v7, v150
	v_add_f32_e32 v149, v147, v151
	v_sub_f32_e32 v147, v147, v151
	v_sub_f32_e32 v7, v7, v150
	v_add_f32_e32 v150, v160, v182
	v_add_f32_e32 v151, v161, v183
	v_sub_f32_e32 v161, v161, v183
	v_sub_f32_e32 v160, v160, v182
	v_add_f32_e32 v183, v158, v172
	v_sub_f32_e32 v158, v158, v172
	v_add_f32_e32 v172, v140, v138
	v_sub_f32_e32 v138, v140, v138
	v_xor_b32_e32 v160, 0x80000000, v160
	v_add_f32_e32 v182, v159, v173
	v_sub_f32_e32 v159, v159, v173
	v_add_f32_e32 v173, v141, v139
	v_sub_f32_e32 v139, v141, v139
	v_xor_b32_e32 v138, 0x80000000, v138
	v_add_f32_e32 v140, v184, v168
	v_add_f32_e32 v141, v185, v169
	v_add_f32_e32 v200, v171, v165
	v_add_f32_e32 v201, v170, v164
; __device__ __forceinline__ unsigned cvt_pk_bf16(float lo, float hi) { f32x2_t v = {lo, hi}; bf16x2_t b = __builtin_convertvector(v, bf16x2_t); return __builtin_bit_cast(unsigned, b); }
; #define LAS __attribute__((address_space(3)))
; __device__ __forceinline__ void fft_phase(Frame& F, const bf16* Yc, bf16* Y) {
;     ...
;               fft_dif<32, 5>(re, im);
; #pragma unroll
;               for (int k = 0; k < 32; ++k) *(LAS unsigned*)(l3 + 4 * c + 16 * k) = pg8::cvt_pk_bf16(re[BR5[k]], im[BR5[k]]); } }
;         __syncthreads();
;         bf16* dst = Y + ((size_t)b * SEQ) * 1024 + 128 * g;
;         const float sc1 = 1.0f / 1024.0f;
; #pragma unroll 2
;         for (int i = 0; i < 16; ++i) { const int k = t + 512 * i, km = (SEQ - k) & (SEQ - 1);
	v_sub_f32_e32 v164, v170, v164
	v_sub_f32_e32 v165, v171, v165
	v_add_f32_e32 v170, v156, v2
	v_add_f32_e32 v171, v157, v3
	v_sub_f32_e32 v3, v157, v3
	v_sub_f32_e32 v2, v156, v2
	v_add_f32_e32 v156, v4, v142
	v_add_f32_e32 v157, v5, v143
	v_sub_f32_e32 v5, v5, v143
	v_sub_f32_e32 v4, v4, v142
	v_sub_f32_e32 v169, v185, v169
	v_sub_f32_e32 v168, v184, v168
	v_add_f32_e32 v184, v198, v202
	v_add_f32_e32 v185, v199, v203
	v_sub_f32_e32 v198, v198, v202
	v_add_f32_e32 v142, v8, v154
	v_add_f32_e32 v143, v9, v155
	v_sub_f32_e32 v9, v9, v155
	v_sub_f32_e32 v8, v8, v154
	v_add_f32_e32 v154, v176, v180
	v_add_f32_e32 v155, v177, v181
	v_sub_f32_e32 v177, v177, v181
	v_sub_f32_e32 v176, v176, v180
	v_add_f32_e32 v180, v175, v145
	v_add_f32_e32 v181, v174, v144
	v_sub_f32_e32 v144, v174, v144
	v_sub_f32_e32 v145, v175, v145
	v_add_f32_e32 v174, v152, v186
	v_add_f32_e32 v175, v153, v187
	v_sub_f32_e32 v153, v153, v187
	v_sub_f32_e32 v152, v152, v186
	v_add_f32_e32 v186, v162, v189
	v_add_f32_e32 v187, v163, v188
	v_sub_f32_e32 v163, v163, v188
	v_sub_f32_e32 v162, v162, v189
	v_add_f32_e32 v188, v190, v192
	v_add_f32_e32 v189, v191, v193
	v_sub_f32_e32 v191, v191, v193
	v_sub_f32_e32 v190, v190, v192
	v_add_f32_e32 v192, v179, v6
	v_add_f32_e32 v193, v178, v146
	v_sub_f32_e32 v146, v178, v146
	v_sub_f32_e32 v6, v179, v6
	v_add_f32_e32 v178, v148, v150
	v_add_f32_e32 v179, v149, v151
	v_sub_f32_e32 v149, v149, v151
	v_sub_f32_e32 v148, v148, v150
	v_sub_f32_e32 v199, v199, v203
	v_xor_b32_e32 v198, 0x80000000, v198
	v_add_f32_e32 v150, v7, v161
	v_add_f32_e32 v151, v147, v160
	v_sub_f32_e32 v147, v147, v160
	v_sub_f32_e32 v7, v7, v161
	v_add_f32_e32 v160, v182, v172
	v_add_f32_e32 v161, v183, v173
	v_sub_f32_e32 v173, v183, v173
	v_sub_f32_e32 v172, v182, v172
	v_add_f32_e32 v182, v159, v139
	v_add_f32_e32 v183, v158, v138
	v_sub_f32_e32 v138, v158, v138
	v_sub_f32_e32 v139, v159, v139
	v_add_f32_e32 v158, v140, v184
	v_add_f32_e32 v159, v141, v185
	v_sub_f32_e32 v141, v141, v185
	v_sub_f32_e32 v140, v140, v184
	v_cvt_pk_bf16_f32 v4, v4, v5
	v_cvt_pk_bf16_f32 v5, v148, v149
	ds_write2_b32 v11, v4, v5 offset0:64 offset1:68
	v_cvt_pk_bf16_f32 v4, v152, v153
	v_cvt_pk_bf16_f32 v5, v140, v141
	v_add_f32_e32 v184, v168, v199
	v_add_f32_e32 v185, v169, v198
	v_sub_f32_e32 v169, v169, v198
	v_sub_f32_e32 v168, v168, v199
	v_add_f32_e32 v198, v200, v170
	v_add_f32_e32 v199, v201, v171
	v_sub_f32_e32 v171, v201, v171
	v_sub_f32_e32 v170, v200, v170
	ds_write2_b32 v11, v4, v5 offset0:72 offset1:76
	v_cvt_pk_bf16_f32 v4, v176, v177
	v_cvt_pk_bf16_f32 v5, v172, v173
	v_xor_b32_e32 v2, 0x80000000, v2
	ds_write2_b32 v11, v4, v5 offset0:80 offset1:84
	v_cvt_pk_bf16_f32 v4, v190, v191
	v_cvt_pk_bf16_f32 v5, v170, v171
	v_cvt_pk_bf16_f32 v142, v142, v143
	v_cvt_pk_bf16_f32 v143, v150, v151
	ds_write2_b32 v11, v4, v5 offset0:88 offset1:92
	v_cvt_pk_bf16_f32 v4, v8, v9
	v_cvt_pk_bf16_f32 v5, v7, v147
	s_nop 0
	v_add_f32_e32 v201, v164, v2
	v_sub_f32_e32 v2, v164, v2
	ds_write2_b32 v11, v142, v143 offset0:32 offset1:36
	v_cvt_pk_bf16_f32 v142, v186, v187
	v_cvt_pk_bf16_f32 v143, v184, v185
	ds_write2_b32 v11, v4, v5 offset0:96 offset1:100
	v_cvt_pk_bf16_f32 v4, v162, v163
	v_cvt_pk_bf16_f32 v5, v168, v169
	s_nop 0
	v_add_f32_e32 v200, v165, v3
	v_sub_f32_e32 v3, v165, v3
	v_cvt_pk_bf16_f32 v156, v156, v157
	v_cvt_pk_bf16_f32 v157, v178, v179
	v_cvt_pk_bf16_f32 v154, v154, v155
	v_cvt_pk_bf16_f32 v155, v160, v161
	ds_write2_b32 v11, v142, v143 offset0:40 offset1:44
	v_cvt_pk_bf16_f32 v142, v180, v181
	v_cvt_pk_bf16_f32 v143, v182, v183
	ds_write2_b32 v11, v4, v5 offset0:104 offset1:108
	v_cvt_pk_bf16_f32 v4, v145, v144
	v_cvt_pk_bf16_f32 v5, v139, v138
	ds_write2_b32 v11, v156, v157 offset1:4
	v_cvt_pk_bf16_f32 v156, v174, v175
	v_cvt_pk_bf16_f32 v157, v158, v159
	ds_write2_b32 v11, v154, v155 offset0:16 offset1:20
	v_cvt_pk_bf16_f32 v154, v188, v189
	v_cvt_pk_bf16_f32 v155, v198, v199
	ds_write2_b32 v11, v142, v143 offset0:48 offset1:52
	v_cvt_pk_bf16_f32 v142, v192, v193
	v_cvt_pk_bf16_f32 v143, v200, v201
	ds_write2_b32 v11, v4, v5 offset0:112 offset1:116
	v_cvt_pk_bf16_f32 v4, v6, v146
	v_cvt_pk_bf16_f32 v2, v3, v2
	s_mov_b32 s0, 4
	s_mov_b64 s[4:5], 0
	s_and_b64 vcc, exec, vcc
	ds_write2_b32 v11, v156, v157 offset0:8 offset1:12
	ds_write2_b32 v11, v154, v155 offset0:24 offset1:28
	ds_write2_b32 v11, v142, v143 offset0:56 offset1:60
	ds_write2_b32 v11, v4, v2 offset0:120 offset1:124
	s_cbranch_vccz .LBB0_201
	s_and_b32 s2, s16, 15
	s_lshl_b32 s18, s2, 3
	s_ashr_i32 s2, s17, 7
	s_and_b32 s0, s9, 7
	s_ashr_i32 s3, s2, 31
	s_lshl_b32 s0, s0, 8
	s_lshl_b64 s[2:3], s[2:3], 17
	s_add_u32 s4, s74, s2
	s_addc_u32 s5, s75, s3
	s_lshl_b32 s6, s8, 22
	s_add_u32 s4, s4, s6
	s_addc_u32 s5, s5, 0
	s_lshl_b32 s6, s10, 18
	s_add_u32 s4, s4, s6
	s_addc_u32 s5, s5, 0
	s_cmp_eq_u32 s10, 0
	s_cselect_b64 s[6:7], -1, 0
	s_cmp_lg_u32 s10, 0
	s_cselect_b64 s[8:9], -1, 0
	s_lshl_b32 s19, s10, 2
	s_sub_u32 s12, 0, s19
	s_subb_u32 s13, 0, 0
	s_or_b32 s2, s2, s0
	s_sub_u32 s14, s2, s18
	s_subb_u32 s15, s3, 0
	v_lshl_add_u64 v[138:139], v[134:135], 0, s[14:15]
	s_lshl_b32 s14, s18, 1
	s_or_b32 s14, s2, s14
	s_mov_b32 s15, s3
	s_mov_b64 s[10:11], 0
	v_lshl_add_u64 v[140:141], v[136:137], 0, s[14:15]
	v_lshl_add_u64 v[142:143], v[134:135], 0, s[2:3]
	s_lshl_b32 s0, s19, 2
	v_mov_b32_e32 v11, v197
	v_mov_b32_e32 v148, v10
	s_mov_b32 s18, 0x5040100
	s_waitcnt lgkmcnt(0)
	s_barrier
	s_branch .LBB0_204

; __device__ __forceinline__ unsigned cvt_pk_bf16(float lo, float hi) { f32x2_t v = {lo, hi}; bf16x2_t b = __builtin_convertvector(v, bf16x2_t); return __builtin_bit_cast(unsigned, b); }
; #define GAS __attribute__((address_space(1)))
; #define LAS __attribute__((address_space(3)))
; __device__ __forceinline__ void fft_phase(Frame& F, const bf16* Yc, bf16* Y) {
;     ...
;         for (int i = 0; i < 16; ++i) { const int k = t + 512 * i, km = (SEQ - k) & (SEQ - 1);
;             const v4u v = *(const LAS v4u*)(buf + fft_slot(k)), w = *(const LAS v4u*)(buf + fft_slot(km));
;             float d0 = bflo(v.x) * sc1, m0 = bflo(w.x) * sc1;
;             if (q4 == 0) { d0 = 0.5f * sc1 * (bflo(v.x) + bflo(w.x)); m0 = 0.5f * sc1 * (bfhi(v.x) + bfhi(w.x)); }
;             bf16* row = dst + (size_t)k * 1024;
;             v2u o; o.x = pg8::cvt_pk_bf16(d0, bflo(v.y) * sc1); o.y = pg8::cvt_pk_bf16(bflo(v.z) * sc1, bflo(v.w) * sc1);
;             *(GAS v2u*)(row + 4 * q4) = o;
;             const unsigned m12 = pg8::cvt_pk_bf16(bflo(w.z) * sc1, bflo(w.y) * sc1);
;             const unsigned m3 = pg8::cvt_pk_bf16(bflo(w.w) * sc1, 0.f) & 0xffffu, mz = pg8::cvt_pk_bf16(m0, 0.f) & 0xffffu;
;             if (q4 != 0) { P8u o2; o2.a = m3 | (m12 << 16); o2.b = (m12 >> 16) | (mz << 16); *(P8u*)(row + 125 - 4 * q4) = o2; }
;             else { row[125] = (bf16)m3; *(GAS unsigned*)(row + 126) = m12; row[64] = (bf16)mz; }
.LBB0_207:
	v_lshlrev_b32_e32 v2, 16, v7
	v_lshlrev_b32_e32 v9, 16, v9
	v_lshlrev_b32_e32 v8, 16, v8
	v_mul_f32_e32 v2, 0x3a800000, v2
	v_pk_mul_f32 v[8:9], v[8:9], s[64:65] op_sel_hi:[1,0]
	v_cvt_pk_bf16_f32 v6, v144, v2
	v_cvt_pk_bf16_f32 v7, v8, v9
	v_lshlrev_b32_e32 v147, 16, v4
	v_lshlrev_b32_e32 v146, 16, v3
	v_pk_mul_f32 v[2:3], v[146:147], s[64:65] op_sel_hi:[1,0]
	s_nop 0
	v_pk_mov_b32 v[2:3], v[2:3], v[2:3] op_sel:[1,0]
	v_cvt_pk_bf16_f32 v3, v2, v3
	v_lshlrev_b32_e32 v2, 16, v5
	v_mul_f32_e32 v2, 0x3a800000, v2
	v_cvt_pk_bf16_f32 v4, v2, 0
	v_cvt_pk_bf16_f32 v2, v145, 0
	v_and_b32_e32 v5, 0xffff, v4
	v_lshl_or_b32 v8, v3, 16, v5
	v_alignbit_b32 v9, v2, v3, 16
	v_lshlrev_b32_e32 v152, 4, v148
	v_mov_b32_e32 v153, 0
	v_lshl_add_u64 v[152:153], s[4:5], 0, v[152:153]
	global_store_dwordx4 v[152:153], v[6:9], off

; __device__ __forceinline__ unsigned cvt_pk_bf16(float lo, float hi) { f32x2_t v = {lo, hi}; bf16x2_t b = __builtin_convertvector(v, bf16x2_t); return __builtin_bit_cast(unsigned, b); }
; #define GAS __attribute__((address_space(1)))
; #define LAS __attribute__((address_space(3)))
; __device__ __forceinline__ void fft_phase(Frame& F, const bf16* Yc, bf16* Y) {
;     ...
;         for (int i = 0; i < 16; ++i) { const int k = t + 512 * i, km = (SEQ - k) & (SEQ - 1);
;             const v4u v = *(const LAS v4u*)(buf + fft_slot(k)), w = *(const LAS v4u*)(buf + fft_slot(km));
;             float d0 = bflo(v.x) * sc1, m0 = bflo(w.x) * sc1;
;             if (q4 == 0) { d0 = 0.5f * sc1 * (bflo(v.x) + bflo(w.x)); m0 = 0.5f * sc1 * (bfhi(v.x) + bfhi(w.x)); }
;             bf16* row = dst + (size_t)k * 1024;
;             v2u o; o.x = pg8::cvt_pk_bf16(d0, bflo(v.y) * sc1); o.y = pg8::cvt_pk_bf16(bflo(v.z) * sc1, bflo(v.w) * sc1);
;             *(GAS v2u*)(row + 4 * q4) = o;
;             const unsigned m12 = pg8::cvt_pk_bf16(bflo(w.z) * sc1, bflo(w.y) * sc1);
;             const unsigned m3 = pg8::cvt_pk_bf16(bflo(w.w) * sc1, 0.f) & 0xffffu, mz = pg8::cvt_pk_bf16(m0, 0.f) & 0xffffu;
;             if (q4 != 0) { P8u o2; o2.a = m3 | (m12 << 16); o2.b = (m12 >> 16) | (mz << 16); *(P8u*)(row + 125 - 4 * q4) = o2; }
;             else { row[125] = (bf16)m3; *(GAS unsigned*)(row + 126) = m12; row[64] = (bf16)mz; }
.LBB0_214:
	v_ashrrev_i32_e32 v145, 31, v144
	v_lshlrev_b64 v[144:145], 4, v[144:145]
	v_lshlrev_b32_e32 v2, 16, v7
	v_lshlrev_b32_e32 v9, 16, v9
	v_lshlrev_b32_e32 v8, 16, v8
	v_lshl_add_u64 v[144:145], s[4:5], 0, v[144:145]
	v_mul_f32_e32 v2, 0x3a800000, v2
	v_pk_mul_f32 v[8:9], v[8:9], s[64:65] op_sel_hi:[1,0]
	v_cvt_pk_bf16_f32 v6, v146, v2
	v_cvt_pk_bf16_f32 v7, v8, v9
	v_lshlrev_b32_e32 v151, 16, v4
	v_lshlrev_b32_e32 v150, 16, v3
	v_pk_mul_f32 v[2:3], v[150:151], s[64:65] op_sel_hi:[1,0]
	s_nop 0
	v_pk_mov_b32 v[2:3], v[2:3], v[2:3] op_sel:[1,0]
	v_cvt_pk_bf16_f32 v2, v2, v3
	v_lshlrev_b32_e32 v3, 16, v5
	v_mul_f32_e32 v3, 0x3a800000, v3
	v_cvt_pk_bf16_f32 v4, v3, 0
	v_cvt_pk_bf16_f32 v3, v147, 0
	v_and_b32_e32 v5, 0xffff, v4
	v_lshl_or_b32 v8, v2, 16, v5
	v_alignbit_b32 v9, v3, v2, 16
	v_mov_b64_e32 v[150:151], v[144:145]
	global_store_dwordx4 v[150:151], v[6:9], off
	s_branch .LBB0_203

; #define PG8_STAGE(bufoff, gbase, voff) do { _Pragma("unroll") for (int _i = 0; _i < 2; ++_i) \
;         __builtin_amdgcn_global_load_lds((const unsigned*)((const char*)(gbase) + (voff)[_i]), (PG8_LAS unsigned*)(lds + (bufoff) + ldsw + _i * 8192), 16, 0, 0); } while (0)
; #define PG8_WAIT_V(n) asm volatile("s_waitcnt vmcnt(" #n ")" ::: "memory")
; #define PG8_BAR __builtin_amdgcn_s_barrier()
;     ...
;     unsigned voffA[2], voffB[2];
; #pragma unroll
;     for (int i = 0; i < 2; ++i) { int R, C; stage_rc(tid * 16 + i * 8192, R, C); const int Rb = Epi::PERM ? ((R & ~31) + perm32(R & 31)) : R;
;         voffA[i] = (unsigned)(R * (LDA ? LDA : K) + C) * 2u; voffB[i] = (unsigned)(Rb * K + C) * 2u; }
;     const size_t kstep = (size_t)(BK * 2);
;     const size_t hstepB = (size_t)HALF * K * 2, hstepA = LDA ? (size_t)HALF * LDA * 2 : hstepB;
;     const size_t tstepA = 2 * hstepA, tstepB = 2 * hstepB; constexpr size_t acolB = (size_t)ACOL * 2;
;     ...
;     const char* cA = (const char*)gA + (size_t)cur.pm * tstepA + (size_t)cur.pn * acolB; const char* cB = (const char*)gB + (size_t)cur.pn * tstepB;
;     S.a_ready(cur);
;     if constexpr (SP2) {
;         PG8_STAGE(PG8_SB(0, 0), cB, voffB); PG8_STAGE(PG8_SB(0, 1), cB + hstepB, voffB); PG8_STAGE(PG8_SA(0, 0), cA, voffA); PG8_STAGE(PG8_SA(0, 1), cA + hstepA, voffA);
;         if (wr == 1) PG8_BAR;
;         PG8_WAIT_V(2); PG8_BAR;
;         PG8_STAGE(PG8_SB(1, 0), cB + kstep, voffB); PG8_STAGE(PG8_SA(1, 0), cA + kstep, voffA); PG8_STAGE(PG8_SB(1, 1), cB + hstepB + kstep, voffB);
;         PG8_WAIT_V(6); PG8_BAR;
.LBB0_502:
	v_readlane_b32 s2, v254, 53
	v_readlane_b32 s3, v254, 54
	s_and_b64 s[2:3], s[2:3], exec
	v_readlane_b32 s0, v253, 44
	v_readlane_b32 s2, v253, 46
	s_cselect_b32 s0, s2, s0
	v_readlane_b32 s2, v253, 43
	v_readlane_b32 s3, v253, 45
	s_cselect_b32 s2, s3, s2
	s_lshl_b32 s3, s76, 21
	s_add_u32 s44, s2, s3
	v_readlane_b32 s2, v252, 27
	v_mov_b32_e32 v2, v0
	v_readlane_b32 s3, v252, 28
	s_addc_u32 s45, s0, 0
	s_movk_i32 s10, 0x400
	v_readfirstlane_b32 s20, v2
	s_mov_b64 s[58:59], s[74:75]
	s_andn2_b64 vcc, exec, s[2:3]
	v_writelane_b32 v255, s16, 17
	s_cbranch_vccnz .LBB0_543
	s_waitcnt lgkmcnt(0)
	v_lshlrev_b32_e32 v3, 4, v2
	v_add_u32_e32 v4, 0x2000, v3
	v_ashrrev_i32_e32 v5, 31, v4
	v_lshrrev_b32_e32 v5, 22, v5
	v_add_u32_e32 v5, v4, v5
	v_ashrrev_i32_e32 v5, 10, v5
	v_mul_i32_i24_e32 v6, 0x400, v5
	v_sub_u32_e32 v4, v4, v6
	v_lshrrev_b32_e32 v6, 4, v4
	v_bitop3_b32 v6, v6, v4, 32 bitop3:0x6c
	v_ashrrev_i32_e32 v4, 31, v6
	v_lshrrev_b32_e32 v4, 26, v4
	v_add_u32_e32 v7, v6, v4
	v_lshlrev_b32_e32 v8, 3, v5
	v_ashrrev_i32_e32 v4, 6, v7
	v_and_b32_e32 v8, 0x7ffffff0, v8
	v_add_u32_e32 v8, v4, v8
	v_lshlrev_b32_e32 v4, 5, v5
	v_and_b32_e32 v4, 32, v4
	v_mad_u64_u32 v[4:5], s[2:3], v8, s10, v[4:5]
	v_and_b32_e32 v5, 0xc0, v7
	v_sub_u32_e32 v5, v6, v5
	v_ashrrev_i16_sdwa v5, v243, sext(v5) dst_sel:DWORD dst_unused:UNUSED_PAD src0_sel:DWORD src1_sel:BYTE_0
	v_bfe_i32 v5, v5, 0, 16
	v_add_lshl_u32 v130, v4, v5, 1
	v_bfe_i32 v4, v2, 27, 1
	v_lshrrev_b32_e32 v4, 22, v4
	v_add_u32_e32 v4, v3, v4
	v_and_b32_e32 v4, 0xfffffc00, v4
	v_sub_u32_e32 v3, v3, v4
	v_lshrrev_b32_e32 v4, 4, v3
	v_ashrrev_i32_e32 v5, 31, v2
	v_bitop3_b32 v3, v4, v3, 32 bitop3:0x6c
	v_lshrrev_b32_e32 v5, 26, v5
	v_ashrrev_i32_e32 v4, 31, v3
	v_add_u32_e32 v5, v2, v5
	v_lshrrev_b32_e32 v4, 26, v4
	v_ashrrev_i32_e32 v5, 6, v5
	v_add_u32_e32 v6, v3, v4
	v_lshlrev_b32_e32 v7, 3, v5
	v_ashrrev_i32_e32 v4, 6, v6
	v_and_b32_e32 v7, 0x7ffffff0, v7
	v_add_u32_e32 v7, v4, v7
	v_lshlrev_b32_e32 v4, 5, v5
	s_ashr_i32 s11, s10, 31
	v_and_b32_e32 v4, 32, v4
	v_readlane_b32 s8, v254, 25
	s_lshl_b64 s[72:73], s[10:11], 9
	v_mad_u64_u32 v[4:5], s[2:3], v7, s10, v[4:5]
	v_readlane_b32 s9, v254, 26
	s_mul_i32 s2, s72, s9
	s_mul_hi_u32 s3, s72, s8
	s_add_i32 s6, s3, s2
	s_lshr_b64 s[2:3], s[10:11], 23
	v_readlane_b32 s12, v254, 29
	s_mul_i32 s3, s2, s8
	v_readlane_b32 s13, v254, 30
	s_add_i32 s3, s6, s3
	s_mul_i32 s6, s72, s13
	s_mul_hi_u32 s7, s72, s12
	s_ashr_i32 s16, s20, 6
	v_and_b32_e32 v5, 0xc0, v6
	s_add_i32 s6, s7, s6
	s_mul_i32 s2, s2, s12
	s_ashr_i32 s17, s20, 8
	s_lshl_b64 s[60:61], s[10:11], 8
	s_lshl_b32 s0, s16, 10
	v_sub_u32_e32 v3, v3, v5
	s_add_i32 s2, s6, s2
	s_mul_i32 s6, s72, s12
	v_ashrrev_i16_sdwa v3, v243, sext(v3) dst_sel:DWORD dst_unused:UNUSED_PAD src0_sel:DWORD src1_sel:BYTE_0
	s_add_u32 s6, s44, s6
	v_bfe_i32 v3, v3, 0, 16
	s_addc_u32 s7, s45, s2
	s_add_i32 s2, s0, 0
	v_add_lshl_u32 v166, v4, v3, 1
	v_readlane_b32 s101, v254, 52
	s_bitcmp1_b32 s101, 0
	s_cbranch_scc1 .Lop_fourier
	v_mov_b32_e32 v246, v166
	v_mov_b32_e32 v248, v130
	v_mov_b32_e32 v244, 0x80
	s_movk_i32 s101, 0x80
	v_writelane_b32 v255, s101, 40
	s_movk_i32 s101, 0x100
	v_writelane_b32 v255, s101, 41
	s_mov_b32 s101, 0x40000
	s_branch .Lop_setdone
.Lop_fourier:
	v_bfe_u32 v246, v166, 4, 3
	v_lshrrev_b32_e32 v247, 11, v166
	v_lshlrev_b32_e32 v246, 18, v246
	v_lshl_or_b32 v246, v247, 4, v246
	v_bfe_u32 v248, v130, 4, 3
	v_lshrrev_b32_e32 v249, 11, v130
	v_lshlrev_b32_e32 v248, 18, v248
	v_lshl_or_b32 v248, v249, 4, v248
	v_mov_b32_e32 v244, 0x200000
	s_mov_b32 s101, 0x200000
	v_writelane_b32 v255, s101, 40
	s_mov_b32 s101, 0x400000
	v_writelane_b32 v255, s101, 41
	s_movk_i32 s101, 0x800
.Lop_setdone:
	v_mov_b32_e32 v245, 0
	v_mov_b32_e32 v247, 0
	v_mov_b32_e32 v249, 0
	s_add_i32 m0, s2, 0x10000
	s_mul_i32 s8, s72, s8
	global_load_lds_dwordx4 v166, s[6:7]
	s_add_i32 m0, s2, 0x12000
	s_add_u32 s12, s6, s60
	global_load_lds_dwordx4 v130, s[6:7]
	s_addc_u32 s13, s7, s61
	s_add_i32 m0, s2, 0x14000
	s_nop 0
	global_load_lds_dwordx4 v166, s[12:13]
	s_add_i32 m0, s2, 0x16000
	s_add_u32 s8, s58, s8
	s_addc_u32 s9, s59, s3
	s_cmpk_lg_u32 s101, 0x800
	s_cbranch_scc1 .Lop_base_done
	v_readlane_b32 s8, v254, 25
	s_lshl_b32 s8, s8, 12
	s_add_u32 s8, s58, s8
	s_addc_u32 s9, s59, 0
.Lop_base_done:
	s_add_i32 s3, s2, 0x2000
	global_load_lds_dwordx4 v130, s[12:13]
	s_mov_b32 m0, s2
	s_add_u32 s18, s8, s101
	global_load_lds_dwordx4 v246, s[8:9]
	s_mov_b32 m0, s3
	s_addc_u32 s19, s9, 0
	s_add_i32 s14, s2, 0x4000
	global_load_lds_dwordx4 v248, s[8:9]
	s_mov_b32 m0, s14
	s_add_i32 s15, s2, 0x6000
	global_load_lds_dwordx4 v246, s[18:19]
	s_mov_b32 m0, s15
	s_cmp_eq_u32 s17, 1
	global_load_lds_dwordx4 v248, s[18:19]
	s_cselect_b64 s[86:87], -1, 0
	s_cmp_lg_u32 s17, 1
	s_cbranch_scc1 .LBB0_505
	s_barrier
.LBB0_505:
	v_bfe_u32 v16, v2, 4, 2
	s_lshr_b32 s11, s11, 26
	v_mov_b32_e32 v131, v167
	v_and_b32_e32 v228, 15, v2
	s_add_i32 s11, s10, s11
	v_lshlrev_b32_e32 v3, 4, v16
	v_lshlrev_b32_e32 v2, 2, v2
	v_lshl_add_u64 v[8:9], s[12:13], 0, v[166:167]
	v_lshl_add_u64 v[10:11], s[12:13], 0, v[130:131]
	s_and_b32 s12, s16, 3
	s_ashr_i32 s13, s11, 6
	v_lshl_or_b32 v3, v228, 6, v3
	s_lshl_b32 s11, s17, 13
	v_and_b32_e32 v2, 32, v2
	v_lshl_add_u64 v[4:5], s[6:7], 0, v[166:167]
	v_bitop3_b32 v17, v3, s11, v2 bitop3:0xde
	s_lshl_b32 s11, s12, 12
	v_lshl_add_u64 v[6:7], s[6:7], 0, v[130:131]
	v_bitop3_b32 v229, v3, s11, v2 bitop3:0xde
	s_add_i32 m0, s2, 0x18000
	v_lshl_add_u64 v[2:3], v[4:5], 0, s[62:63]
	v_lshl_add_u64 v[12:13], s[8:9], 0, v[246:247]
	s_lshl_b32 s16, s17, 6
	s_waitcnt vmcnt(2)
	s_barrier
	global_load_lds_dwordx4 v[2:3], off
	v_lshl_add_u64 v[2:3], v[6:7], 0, s[62:63]
	s_add_i32 m0, s2, 0x1a000
	s_add_i32 s17, s2, 0x8000
	v_lshl_add_u64 v[14:15], s[8:9], 0, v[248:249]
	global_load_lds_dwordx4 v[2:3], off
	v_lshl_add_u64 v[2:3], v[12:13], 0, v[244:245]
	s_mov_b32 m0, s17
	s_add_i32 s18, s2, 0xa000
	global_load_lds_dwordx4 v[2:3], off
	v_lshl_add_u64 v[2:3], v[14:15], 0, v[244:245]
	s_mov_b32 m0, s18
	v_cmp_eq_u32_e64 s[38:39], 0, v16
	global_load_lds_dwordx4 v[2:3], off
	s_add_i32 m0, s2, 0x1c000
	v_lshl_add_u64 v[2:3], v[8:9], 0, s[62:63]
	global_load_lds_dwordx4 v[2:3], off
	v_lshl_add_u64 v[2:3], v[10:11], 0, s[62:63]
	s_add_i32 m0, s2, 0x1e000
	s_cmp_gt_i32 s10, 63
	global_load_lds_dwordx4 v[2:3], off
	s_waitcnt vmcnt(6)
	s_cselect_b64 s[88:89], -1, 0
	s_add_i32 s19, s13, -2
	s_cmpk_lt_u32 s20, 0x100
	v_lshlrev_b32_e32 v2, 2, v16
	v_readlane_b32 s10, v254, 25
	s_cselect_b64 s[90:91], -1, 0
	v_lshl_or_b32 v230, s12, 5, v2
	s_mov_b32 s20, 0
	v_add_u32_e32 v132, s101, v248
	v_mov_b32_e32 v133, 0
	v_add_u32_e32 v134, s101, v246
	v_mov_b32_e32 v135, 0
	v_add_u32_e32 v231, 0, v17
	v_readlane_b32 s23, v254, 13
	s_mov_b32 s24, s10
	s_barrier
	v_readlane_b32 s11, v254, 26
	s_branch .LBB0_508

; #define PG8_STAGE(bufoff, gbase, voff) do { _Pragma("unroll") for (int _i = 0; _i < 2; ++_i) \
;         __builtin_amdgcn_global_load_lds((const unsigned*)((const char*)(gbase) + (voff)[_i]), (PG8_LAS unsigned*)(lds + (bufoff) + ldsw + _i * 8192), 16, 0, 0); } while (0)
; #define PG8_LDA(dst, b, h) do { _Pragma("unroll") for (int m = 0; m < 4; ++m) _Pragma("unroll") for (int k = 0; k < 2; ++k) dst[m][k] = *(const PG8_LAS bf16x8*)(lds + PG8_SA(b, h) + aoff + m * 2048 + k * 1024); } while (0)
; #define PG8_LDB(dst, b, h) do { _Pragma("unroll") for (int n = 0; n < 2; ++n) _Pragma("unroll") for (int k = 0; k < 2; ++k) dst[n][k] = *(const PG8_LAS bf16x8*)(lds + PG8_SB(b, h) + boff + n * 2048 + k * 1024); } while (0)
; #define PG8_MMA(ai, bj, At, Bt) do { __builtin_amdgcn_s_setprio(1); _Pragma("unroll") for (int m = 0; m < 4; ++m) _Pragma("unroll") for (int n = 0; n < 2; ++n) _Pragma("unroll") for (int k = 0; k < 2; ++k) \
;         acc[ai][bj][m][n] = __builtin_amdgcn_mfma_f32_16x16x32_bf16(Bt[n][k], At[m][k], acc[ai][bj][m][n], 0, 0, 0); __builtin_amdgcn_s_setprio(0); } while (0)
; #define PG8_WAIT_V(n) asm volatile("s_waitcnt vmcnt(" #n ")" ::: "memory")
; #define PG8_WAIT_L(n) asm volatile("s_waitcnt lgkmcnt(" #n ")" ::: "memory")
; #define PG8_BAR __builtin_amdgcn_s_barrier()
; #define PG8_SCHED __builtin_amdgcn_sched_barrier(0)
;     ...
;         for (int t = 0; t < nt; t += 2) {
;             const bool last = (t == nt - 2);
;             const char* a1 = cA + (size_t)(t + 1) * kstep;
;             const char* a2 = last ? nA : cA + (size_t)(t + 2) * kstep; const char* b2 = last ? nB : cB + (size_t)(t + 2) * kstep;
;             const char* a3 = a2 + kstep; const char* b3 = b2 + kstep;
;             if (last && has_next) S.a_ready(nxt);
;             if constexpr (SP2) {
;             PG8_LDB(B0, 0, 0); PG8_LDB(B1, 0, 1); PG8_SCHED; PG8_LDA(At, 0, 0); PG8_STAGE(PG8_SA(1, 1), a1 + hstepA, voffA);
;             PG8_WAIT_V(8); PG8_WAIT_L(0); PG8_BAR; PG8_MMA(0, 0, At, B0); PG8_MMA(0, 1, At, B1); PG8_BAR; PG8_SCHED;
;             PG8_LDA(At, 0, 1); PG8_STAGE(PG8_SB(0, 0), b2, voffB); PG8_STAGE(PG8_SB(0, 1), b2 + hstepB, voffB); PG8_STAGE(PG8_SA(0, 0), a2, voffA);
;             PG8_WAIT_V(8); PG8_WAIT_L(0); PG8_BAR; PG8_MMA(1, 0, At, B0); PG8_MMA(1, 1, At, B1); PG8_BAR; PG8_SCHED;
.LBB0_518:
	s_andn2_b64 vcc, exec, s[88:89]
	s_waitcnt lgkmcnt(0)
	s_cbranch_vccnz .LBB0_521
	s_add_u32 s10, s6, 0x100
	s_addc_u32 s11, s7, 0
	v_readlane_b32 s6, v255, 40
	s_add_u32 s6, s8, s6
	s_addc_u32 s7, s9, 0
	s_mov_b32 s8, 0
	s_add_i32 s25, s8, 2
	v_readlane_b32 s27, v255, 40
	s_add_u32 s27, s6, s27
	s_addc_u32 s9, s7, 0
	s_add_i32 s31, 0, 0x10000
	s_cmp_eq_u32 s19, s8
	s_cselect_b32 s9, s43, s9
	s_cselect_b32 s8, s42, s27
	s_cselect_b32 s35, s93, s11
	s_cselect_b32 s34, s92, s10
	s_add_i32 s27, 0, 0x14000
	v_add_u32_e32 v148, s31, v229
	v_add_u32_e32 v164, s27, v229
	ds_read_b128 v[136:139], v148
	ds_read_b128 v[140:143], v148 offset:1024
	ds_read_b128 v[144:147], v148 offset:2048
	ds_read_b128 v[148:151], v148 offset:3072
	ds_read_b128 v[152:155], v164
	ds_read_b128 v[156:159], v164 offset:1024
	ds_read_b128 v[160:163], v164 offset:2048
	ds_read_b128 v[172:175], v164 offset:3072
	v_lshl_add_u64 v[164:165], s[6:7], 0, v[134:135]
	s_add_i32 m0, s2, 0xc000
	ds_read_b128 v[176:179], v231
	ds_read_b128 v[180:183], v231 offset:1024
	ds_read_b128 v[184:187], v231 offset:2048
	ds_read_b128 v[188:191], v231 offset:3072
	ds_read_b128 v[192:195], v231 offset:4096
	ds_read_b128 v[196:199], v231 offset:5120
	ds_read_b128 v[200:203], v231 offset:6144
	ds_read_b128 v[204:207], v231 offset:7168
	global_load_lds_dwordx4 v[164:165], off
	v_lshl_add_u64 v[164:165], s[6:7], 0, v[132:133]
	s_add_i32 m0, s2, 0xe000
	s_nop 0
	global_load_lds_dwordx4 v[164:165], off
	s_waitcnt vmcnt(8)
	s_waitcnt lgkmcnt(0)
	s_barrier
	s_waitcnt lgkmcnt(0)
	v_mfma_f32_16x16x32_bf16 v[126:129], v[136:139], v[176:179], 0
	v_mfma_f32_16x16x32_bf16 v[122:125], v[144:147], v[176:179], 0
	v_mfma_f32_16x16x32_bf16 v[110:113], v[136:139], v[184:187], 0
	v_mfma_f32_16x16x32_bf16 v[106:109], v[144:147], v[184:187], 0
	v_mfma_f32_16x16x32_bf16 v[94:97], v[136:139], v[192:195], 0
	v_mfma_f32_16x16x32_bf16 v[90:93], v[144:147], v[192:195], 0
	v_mfma_f32_16x16x32_bf16 v[78:81], v[136:139], v[200:203], 0
	v_mfma_f32_16x16x32_bf16 v[74:77], v[144:147], v[200:203], 0
	v_mfma_f32_16x16x32_bf16 v[126:129], v[140:143], v[180:183], v[126:129]
	v_mfma_f32_16x16x32_bf16 v[122:125], v[148:151], v[180:183], v[122:125]
	v_mfma_f32_16x16x32_bf16 v[110:113], v[140:143], v[188:191], v[110:113]
	v_mfma_f32_16x16x32_bf16 v[106:109], v[148:151], v[188:191], v[106:109]
	v_mfma_f32_16x16x32_bf16 v[94:97], v[140:143], v[196:199], v[94:97]
	v_mfma_f32_16x16x32_bf16 v[90:93], v[148:151], v[196:199], v[90:93]
	v_mfma_f32_16x16x32_bf16 v[78:81], v[140:143], v[204:207], v[78:81]
	v_mfma_f32_16x16x32_bf16 v[74:77], v[148:151], v[204:207], v[74:77]
	v_mfma_f32_16x16x32_bf16 v[118:121], v[152:155], v[176:179], 0
	v_mfma_f32_16x16x32_bf16 v[114:117], v[160:163], v[176:179], 0
	v_mfma_f32_16x16x32_bf16 v[102:105], v[152:155], v[184:187], 0
	v_mfma_f32_16x16x32_bf16 v[98:101], v[160:163], v[184:187], 0
	v_mfma_f32_16x16x32_bf16 v[86:89], v[152:155], v[192:195], 0
	v_mfma_f32_16x16x32_bf16 v[82:85], v[160:163], v[192:195], 0
	v_mfma_f32_16x16x32_bf16 v[70:73], v[152:155], v[200:203], 0
	v_mfma_f32_16x16x32_bf16 v[66:69], v[160:163], v[200:203], 0
	v_mfma_f32_16x16x32_bf16 v[118:121], v[156:159], v[180:183], v[118:121]
	v_mfma_f32_16x16x32_bf16 v[114:117], v[172:175], v[180:183], v[114:117]
	v_mfma_f32_16x16x32_bf16 v[102:105], v[156:159], v[188:191], v[102:105]
	v_mfma_f32_16x16x32_bf16 v[98:101], v[172:175], v[188:191], v[98:101]
	v_mfma_f32_16x16x32_bf16 v[86:89], v[156:159], v[196:199], v[86:89]
	v_mfma_f32_16x16x32_bf16 v[82:85], v[172:175], v[196:199], v[82:85]
	v_mfma_f32_16x16x32_bf16 v[70:73], v[156:159], v[204:207], v[70:73]
	v_mfma_f32_16x16x32_bf16 v[66:69], v[172:175], v[204:207], v[66:69]
	s_barrier
	s_add_i32 s31, s31, s0
	v_lshl_add_u64 v[164:165], s[34:35], 0, v[166:167]
	s_mov_b32 m0, s31
	ds_read_b128 v[176:179], v231 offset:16384
	ds_read_b128 v[180:183], v231 offset:17408
	ds_read_b128 v[184:187], v231 offset:18432
	ds_read_b128 v[188:191], v231 offset:19456
	ds_read_b128 v[192:195], v231 offset:20480
	ds_read_b128 v[196:199], v231 offset:21504
	ds_read_b128 v[200:203], v231 offset:22528
	ds_read_b128 v[204:207], v231 offset:23552
	global_load_lds_dwordx4 v[164:165], off
	s_add_i32 m0, s31, 0x2000
	v_lshl_add_u64 v[168:169], s[34:35], 0, v[130:131]
	s_add_u32 s34, s34, s60
	s_addc_u32 s35, s35, s61
	s_add_i32 s27, s27, s0
	global_load_lds_dwordx4 v[168:169], off
	v_lshl_add_u64 v[170:171], s[34:35], 0, v[166:167]
	s_mov_b32 m0, s27
	v_lshl_add_u64 v[208:209], s[34:35], 0, v[130:131]
	global_load_lds_dwordx4 v[170:171], off
	s_add_i32 m0, s27, 0x2000
	v_lshl_add_u64 v[210:211], s[8:9], 0, v[246:247]
	global_load_lds_dwordx4 v[208:209], off
	s_mov_b32 m0, s2
	v_lshl_add_u64 v[212:213], s[8:9], 0, v[248:249]
	global_load_lds_dwordx4 v[210:211], off
	s_mov_b32 m0, s3
	s_nop 0
	global_load_lds_dwordx4 v[212:213], off
	s_waitcnt vmcnt(8)
	s_waitcnt lgkmcnt(0)
	s_barrier
; #define PG8_STAGE(bufoff, gbase, voff) do { _Pragma("unroll") for (int _i = 0; _i < 2; ++_i) \
;         __builtin_amdgcn_global_load_lds((const unsigned*)((const char*)(gbase) + (voff)[_i]), (PG8_LAS unsigned*)(lds + (bufoff) + ldsw + _i * 8192), 16, 0, 0); } while (0)
; #define PG8_LDA(dst, b, h) do { _Pragma("unroll") for (int m = 0; m < 4; ++m) _Pragma("unroll") for (int k = 0; k < 2; ++k) dst[m][k] = *(const PG8_LAS bf16x8*)(lds + PG8_SA(b, h) + aoff + m * 2048 + k * 1024); } while (0)
; #define PG8_LDB(dst, b, h) do { _Pragma("unroll") for (int n = 0; n < 2; ++n) _Pragma("unroll") for (int k = 0; k < 2; ++k) dst[n][k] = *(const PG8_LAS bf16x8*)(lds + PG8_SB(b, h) + boff + n * 2048 + k * 1024); } while (0)
; #define PG8_MMA(ai, bj, At, Bt) do { __builtin_amdgcn_s_setprio(1); _Pragma("unroll") for (int m = 0; m < 4; ++m) _Pragma("unroll") for (int n = 0; n < 2; ++n) _Pragma("unroll") for (int k = 0; k < 2; ++k) \
;         acc[ai][bj][m][n] = __builtin_amdgcn_mfma_f32_16x16x32_bf16(Bt[n][k], At[m][k], acc[ai][bj][m][n], 0, 0, 0); __builtin_amdgcn_s_setprio(0); } while (0)
; #define PG8_WAIT_V(n) asm volatile("s_waitcnt vmcnt(" #n ")" ::: "memory")
; #define PG8_WAIT_L(n) asm volatile("s_waitcnt lgkmcnt(" #n ")" ::: "memory")
; #define PG8_BAR __builtin_amdgcn_s_barrier()
; #define PG8_SCHED __builtin_amdgcn_sched_barrier(0)
;     ...
;             PG8_WAIT_V(8); PG8_WAIT_L(0); PG8_BAR; PG8_MMA(1, 0, At, B0); PG8_MMA(1, 1, At, B1); PG8_BAR; PG8_SCHED;
;             PG8_LDB(B0, 1, 0); PG8_LDB(B1, 1, 1); PG8_SCHED; PG8_LDA(At, 1, 0); PG8_STAGE(PG8_SA(0, 1), a2 + hstepA, voffA);
;             PG8_WAIT_V(8); PG8_WAIT_L(0); PG8_BAR; PG8_MMA(0, 0, At, B0); PG8_MMA(0, 1, At, B1); PG8_BAR; PG8_SCHED;
;             PG8_LDA(At, 1, 1); PG8_STAGE(PG8_SB(1, 0), b3, voffB); PG8_STAGE(PG8_SB(1, 1), b3 + hstepB, voffB); PG8_STAGE(PG8_SA(1, 0), a3, voffA);
	s_waitcnt lgkmcnt(0)
	v_mfma_f32_16x16x32_bf16 v[62:65], v[136:139], v[176:179], 0
	v_mfma_f32_16x16x32_bf16 v[58:61], v[144:147], v[176:179], 0
	v_mfma_f32_16x16x32_bf16 v[46:49], v[136:139], v[184:187], 0
	v_mfma_f32_16x16x32_bf16 v[42:45], v[144:147], v[184:187], 0
	v_mfma_f32_16x16x32_bf16 v[30:33], v[136:139], v[192:195], 0
	v_mfma_f32_16x16x32_bf16 v[26:29], v[144:147], v[192:195], 0
	v_mfma_f32_16x16x32_bf16 v[14:17], v[136:139], v[200:203], 0
	v_mfma_f32_16x16x32_bf16 v[10:13], v[144:147], v[200:203], 0
	v_mfma_f32_16x16x32_bf16 v[62:65], v[140:143], v[180:183], v[62:65]
	v_mfma_f32_16x16x32_bf16 v[58:61], v[148:151], v[180:183], v[58:61]
	v_mfma_f32_16x16x32_bf16 v[46:49], v[140:143], v[188:191], v[46:49]
	v_mfma_f32_16x16x32_bf16 v[42:45], v[148:151], v[188:191], v[42:45]
	v_mfma_f32_16x16x32_bf16 v[30:33], v[140:143], v[196:199], v[30:33]
	v_mfma_f32_16x16x32_bf16 v[26:29], v[148:151], v[196:199], v[26:29]
	v_mfma_f32_16x16x32_bf16 v[14:17], v[140:143], v[204:207], v[14:17]
	v_mfma_f32_16x16x32_bf16 v[10:13], v[148:151], v[204:207], v[10:13]
	v_mfma_f32_16x16x32_bf16 v[54:57], v[152:155], v[176:179], 0
	v_mfma_f32_16x16x32_bf16 v[50:53], v[160:163], v[176:179], 0
	v_mfma_f32_16x16x32_bf16 v[38:41], v[152:155], v[184:187], 0
	v_mfma_f32_16x16x32_bf16 v[34:37], v[160:163], v[184:187], 0
	v_mfma_f32_16x16x32_bf16 v[22:25], v[152:155], v[192:195], 0
	v_mfma_f32_16x16x32_bf16 v[18:21], v[160:163], v[192:195], 0
	v_mfma_f32_16x16x32_bf16 v[6:9], v[152:155], v[200:203], 0
	v_mfma_f32_16x16x32_bf16 v[2:5], v[160:163], v[200:203], 0
	v_mfma_f32_16x16x32_bf16 v[54:57], v[156:159], v[180:183], v[54:57]
	v_mfma_f32_16x16x32_bf16 v[50:53], v[172:175], v[180:183], v[50:53]
	v_mfma_f32_16x16x32_bf16 v[38:41], v[156:159], v[188:191], v[38:41]
	v_mfma_f32_16x16x32_bf16 v[34:37], v[172:175], v[188:191], v[34:37]
	v_mfma_f32_16x16x32_bf16 v[22:25], v[156:159], v[196:199], v[22:25]
	v_mfma_f32_16x16x32_bf16 v[18:21], v[172:175], v[196:199], v[18:21]
	v_mfma_f32_16x16x32_bf16 v[6:9], v[156:159], v[204:207], v[6:9]
	v_mfma_f32_16x16x32_bf16 v[2:5], v[172:175], v[204:207], v[2:5]
	s_barrier
	s_add_i32 s27, 0, 0x18000
	s_add_i32 s31, 0, 0x1c000
	v_add_u32_e32 v148, s27, v229
	v_add_u32_e32 v172, s31, v229
	ds_read_b128 v[136:139], v148
	ds_read_b128 v[140:143], v148 offset:1024
	ds_read_b128 v[144:147], v148 offset:2048
	ds_read_b128 v[148:151], v148 offset:3072
	ds_read_b128 v[152:155], v172
	ds_read_b128 v[156:159], v172 offset:1024
	ds_read_b128 v[160:163], v172 offset:2048
	ds_read_b128 v[172:175], v172 offset:3072
	s_add_u32 s8, s8, s101
	s_addc_u32 s9, s9, 0
	s_mov_b32 m0, s14
	v_lshl_add_u64 v[214:215], s[8:9], 0, v[246:247]
	ds_read_b128 v[176:179], v231 offset:32768
	ds_read_b128 v[180:183], v231 offset:33792
	ds_read_b128 v[184:187], v231 offset:34816
	ds_read_b128 v[188:191], v231 offset:35840
	ds_read_b128 v[192:195], v231 offset:36864
	ds_read_b128 v[196:199], v231 offset:37888
	ds_read_b128 v[200:203], v231 offset:38912
	ds_read_b128 v[204:207], v231 offset:39936
	global_load_lds_dwordx4 v[214:215], off
	v_lshl_add_u64 v[214:215], s[8:9], 0, v[248:249]
	s_mov_b32 m0, s15
	s_nop 0
	global_load_lds_dwordx4 v[214:215], off
	s_waitcnt vmcnt(8)
	s_waitcnt lgkmcnt(0)
	s_barrier
	s_waitcnt lgkmcnt(0)
	v_mfma_f32_16x16x32_bf16 v[126:129], v[136:139], v[176:179], v[126:129]
	v_mfma_f32_16x16x32_bf16 v[122:125], v[144:147], v[176:179], v[122:125]
	v_mfma_f32_16x16x32_bf16 v[110:113], v[136:139], v[184:187], v[110:113]
	v_mfma_f32_16x16x32_bf16 v[106:109], v[144:147], v[184:187], v[106:109]
	v_mfma_f32_16x16x32_bf16 v[94:97], v[136:139], v[192:195], v[94:97]
	v_mfma_f32_16x16x32_bf16 v[90:93], v[144:147], v[192:195], v[90:93]
	v_mfma_f32_16x16x32_bf16 v[78:81], v[136:139], v[200:203], v[78:81]
	v_mfma_f32_16x16x32_bf16 v[74:77], v[144:147], v[200:203], v[74:77]
	v_mfma_f32_16x16x32_bf16 v[126:129], v[140:143], v[180:183], v[126:129]
	v_mfma_f32_16x16x32_bf16 v[122:125], v[148:151], v[180:183], v[122:125]
	v_mfma_f32_16x16x32_bf16 v[110:113], v[140:143], v[188:191], v[110:113]
	v_mfma_f32_16x16x32_bf16 v[106:109], v[148:151], v[188:191], v[106:109]
	v_mfma_f32_16x16x32_bf16 v[94:97], v[140:143], v[196:199], v[94:97]
	v_mfma_f32_16x16x32_bf16 v[90:93], v[148:151], v[196:199], v[90:93]
	v_mfma_f32_16x16x32_bf16 v[78:81], v[140:143], v[204:207], v[78:81]
	v_mfma_f32_16x16x32_bf16 v[74:77], v[148:151], v[204:207], v[74:77]
	v_mfma_f32_16x16x32_bf16 v[118:121], v[152:155], v[176:179], v[118:121]
	v_mfma_f32_16x16x32_bf16 v[114:117], v[160:163], v[176:179], v[114:117]
	v_mfma_f32_16x16x32_bf16 v[102:105], v[152:155], v[184:187], v[102:105]
	v_mfma_f32_16x16x32_bf16 v[98:101], v[160:163], v[184:187], v[98:101]
	v_mfma_f32_16x16x32_bf16 v[86:89], v[152:155], v[192:195], v[86:89]
	v_mfma_f32_16x16x32_bf16 v[82:85], v[160:163], v[192:195], v[82:85]
	v_mfma_f32_16x16x32_bf16 v[70:73], v[152:155], v[200:203], v[70:73]
	v_mfma_f32_16x16x32_bf16 v[66:69], v[160:163], v[200:203], v[66:69]
	v_mfma_f32_16x16x32_bf16 v[118:121], v[156:159], v[180:183], v[118:121]
	v_mfma_f32_16x16x32_bf16 v[114:117], v[172:175], v[180:183], v[114:117]
	v_mfma_f32_16x16x32_bf16 v[102:105], v[156:159], v[188:191], v[102:105]
	v_mfma_f32_16x16x32_bf16 v[98:101], v[172:175], v[188:191], v[98:101]
	v_mfma_f32_16x16x32_bf16 v[86:89], v[156:159], v[196:199], v[86:89]
	v_mfma_f32_16x16x32_bf16 v[82:85], v[172:175], v[196:199], v[82:85]
	v_mfma_f32_16x16x32_bf16 v[70:73], v[156:159], v[204:207], v[70:73]
	v_mfma_f32_16x16x32_bf16 v[66:69], v[172:175], v[204:207], v[66:69]
	s_barrier
; #define PG8_STAGE(bufoff, gbase, voff) do { _Pragma("unroll") for (int _i = 0; _i < 2; ++_i) \
;         __builtin_amdgcn_global_load_lds((const unsigned*)((const char*)(gbase) + (voff)[_i]), (PG8_LAS unsigned*)(lds + (bufoff) + ldsw + _i * 8192), 16, 0, 0); } while (0)
; #define PG8_LDA(dst, b, h) do { _Pragma("unroll") for (int m = 0; m < 4; ++m) _Pragma("unroll") for (int k = 0; k < 2; ++k) dst[m][k] = *(const PG8_LAS bf16x8*)(lds + PG8_SA(b, h) + aoff + m * 2048 + k * 1024); } while (0)
; #define PG8_LDB(dst, b, h) do { _Pragma("unroll") for (int n = 0; n < 2; ++n) _Pragma("unroll") for (int k = 0; k < 2; ++k) dst[n][k] = *(const PG8_LAS bf16x8*)(lds + PG8_SB(b, h) + boff + n * 2048 + k * 1024); } while (0)
; #define PG8_MMA(ai, bj, At, Bt) do { __builtin_amdgcn_s_setprio(1); _Pragma("unroll") for (int m = 0; m < 4; ++m) _Pragma("unroll") for (int n = 0; n < 2; ++n) _Pragma("unroll") for (int k = 0; k < 2; ++k) \
;         acc[ai][bj][m][n] = __builtin_amdgcn_mfma_f32_16x16x32_bf16(Bt[n][k], At[m][k], acc[ai][bj][m][n], 0, 0, 0); __builtin_amdgcn_s_setprio(0); } while (0)
; #define PG8_WAIT_V(n) asm volatile("s_waitcnt vmcnt(" #n ")" ::: "memory")
; #define PG8_WAIT_L(n) asm volatile("s_waitcnt lgkmcnt(" #n ")" ::: "memory")
; #define PG8_BAR __builtin_amdgcn_s_barrier()
; #define PG8_SCHED __builtin_amdgcn_sched_barrier(0)
;     ...
;         for (int t = 0; t < nt; t += 2) {
;             const bool last = (t == nt - 2);
;             const char* a1 = cA + (size_t)(t + 1) * kstep;
;             const char* a2 = last ? nA : cA + (size_t)(t + 2) * kstep; const char* b2 = last ? nB : cB + (size_t)(t + 2) * kstep;
;             const char* a3 = a2 + kstep; const char* b3 = b2 + kstep;
;             if (last && has_next) S.a_ready(nxt);
;             if constexpr (SP2) {
;             PG8_LDB(B0, 0, 0); PG8_LDB(B1, 0, 1); PG8_SCHED; PG8_LDA(At, 0, 0); PG8_STAGE(PG8_SA(1, 1), a1 + hstepA, voffA);
;     ...
;             PG8_LDA(At, 1, 1); PG8_STAGE(PG8_SB(1, 0), b3, voffB); PG8_STAGE(PG8_SB(1, 1), b3 + hstepB, voffB); PG8_STAGE(PG8_SA(1, 0), a3, voffA);
;             PG8_WAIT_V(8); PG8_WAIT_L(0); PG8_BAR; PG8_MMA(1, 0, At, B0); PG8_MMA(1, 1, At, B1); PG8_BAR; PG8_SCHED;
	s_add_i32 s8, s27, s0
	v_lshl_add_u64 v[164:165], v[164:165], 0, s[62:63]
	s_mov_b32 m0, s8
	ds_read_b128 v[176:179], v231 offset:49152
	ds_read_b128 v[180:183], v231 offset:50176
	ds_read_b128 v[184:187], v231 offset:51200
	ds_read_b128 v[188:191], v231 offset:52224
	ds_read_b128 v[192:195], v231 offset:53248
	ds_read_b128 v[196:199], v231 offset:54272
	ds_read_b128 v[200:203], v231 offset:55296
	ds_read_b128 v[204:207], v231 offset:56320
	global_load_lds_dwordx4 v[164:165], off
	v_lshl_add_u64 v[164:165], v[168:169], 0, s[62:63]
	s_add_i32 m0, s8, 0x2000
	s_add_i32 s8, s31, s0
	global_load_lds_dwordx4 v[164:165], off
	v_lshl_add_u64 v[164:165], v[170:171], 0, s[62:63]
	s_mov_b32 m0, s8
	s_nop 0
	global_load_lds_dwordx4 v[164:165], off
	v_lshl_add_u64 v[164:165], v[208:209], 0, s[62:63]
	s_add_i32 m0, s8, 0x2000
	s_nop 0
	global_load_lds_dwordx4 v[164:165], off
	v_lshl_add_u64 v[164:165], v[210:211], 0, v[244:245]
	s_mov_b32 m0, s17
	s_nop 0
	global_load_lds_dwordx4 v[164:165], off
	v_lshl_add_u64 v[164:165], v[212:213], 0, v[244:245]
	s_mov_b32 m0, s18
	s_nop 0
	global_load_lds_dwordx4 v[164:165], off
	s_waitcnt vmcnt(8)
	s_waitcnt lgkmcnt(0)
	s_barrier
	s_waitcnt lgkmcnt(0)
	v_mfma_f32_16x16x32_bf16 v[62:65], v[136:139], v[176:179], v[62:65]
	v_mfma_f32_16x16x32_bf16 v[58:61], v[144:147], v[176:179], v[58:61]
	v_mfma_f32_16x16x32_bf16 v[46:49], v[136:139], v[184:187], v[46:49]
	v_mfma_f32_16x16x32_bf16 v[42:45], v[144:147], v[184:187], v[42:45]
	v_mfma_f32_16x16x32_bf16 v[30:33], v[136:139], v[192:195], v[30:33]
	v_mfma_f32_16x16x32_bf16 v[26:29], v[144:147], v[192:195], v[26:29]
	v_mfma_f32_16x16x32_bf16 v[14:17], v[136:139], v[200:203], v[14:17]
	v_mfma_f32_16x16x32_bf16 v[10:13], v[144:147], v[200:203], v[10:13]
	v_mfma_f32_16x16x32_bf16 v[62:65], v[140:143], v[180:183], v[62:65]
	v_mfma_f32_16x16x32_bf16 v[58:61], v[148:151], v[180:183], v[58:61]
	v_mfma_f32_16x16x32_bf16 v[46:49], v[140:143], v[188:191], v[46:49]
	v_mfma_f32_16x16x32_bf16 v[42:45], v[148:151], v[188:191], v[42:45]
	v_mfma_f32_16x16x32_bf16 v[30:33], v[140:143], v[196:199], v[30:33]
	v_mfma_f32_16x16x32_bf16 v[26:29], v[148:151], v[196:199], v[26:29]
	v_mfma_f32_16x16x32_bf16 v[14:17], v[140:143], v[204:207], v[14:17]
	v_mfma_f32_16x16x32_bf16 v[10:13], v[148:151], v[204:207], v[10:13]
	v_mfma_f32_16x16x32_bf16 v[54:57], v[152:155], v[176:179], v[54:57]
	v_mfma_f32_16x16x32_bf16 v[50:53], v[160:163], v[176:179], v[50:53]
	v_mfma_f32_16x16x32_bf16 v[38:41], v[152:155], v[184:187], v[38:41]
	v_mfma_f32_16x16x32_bf16 v[34:37], v[160:163], v[184:187], v[34:37]
	v_mfma_f32_16x16x32_bf16 v[22:25], v[152:155], v[192:195], v[22:25]
	v_mfma_f32_16x16x32_bf16 v[18:21], v[160:163], v[192:195], v[18:21]
	v_mfma_f32_16x16x32_bf16 v[6:9], v[152:155], v[200:203], v[6:9]
	v_mfma_f32_16x16x32_bf16 v[2:5], v[160:163], v[200:203], v[2:5]
	v_mfma_f32_16x16x32_bf16 v[54:57], v[156:159], v[180:183], v[54:57]
	v_mfma_f32_16x16x32_bf16 v[50:53], v[172:175], v[180:183], v[50:53]
	v_mfma_f32_16x16x32_bf16 v[38:41], v[156:159], v[188:191], v[38:41]
	v_mfma_f32_16x16x32_bf16 v[34:37], v[172:175], v[188:191], v[34:37]
	v_mfma_f32_16x16x32_bf16 v[22:25], v[156:159], v[196:199], v[22:25]
	v_mfma_f32_16x16x32_bf16 v[18:21], v[172:175], v[196:199], v[18:21]
	v_mfma_f32_16x16x32_bf16 v[6:9], v[156:159], v[204:207], v[6:9]
	v_mfma_f32_16x16x32_bf16 v[2:5], v[172:175], v[204:207], v[2:5]
	s_barrier
	s_add_u32 s10, s10, 0x100
	s_addc_u32 s11, s11, 0
	v_readlane_b32 s31, v255, 41
	s_add_u32 s6, s6, s31
	s_addc_u32 s7, s7, 0
	s_cmp_ge_i32 s25, s13
	s_mov_b32 s8, s25
	s_cbranch_scc1 .LBB0_521
.LBB0_520:
	s_add_i32 s25, s8, 2
	v_readlane_b32 s27, v255, 40
	s_add_u32 s27, s6, s27
	s_addc_u32 s9, s7, 0
	s_add_i32 s31, 0, 0x10000
	s_cmp_eq_u32 s19, s8
	s_cselect_b32 s9, s43, s9
	s_cselect_b32 s8, s42, s27
	s_cselect_b32 s35, s93, s11
	s_cselect_b32 s34, s92, s10
	s_add_i32 s27, 0, 0x14000
	v_add_u32_e32 v148, s31, v229
	v_add_u32_e32 v164, s27, v229
	ds_read_b128 v[136:139], v148
	ds_read_b128 v[140:143], v148 offset:1024
	ds_read_b128 v[144:147], v148 offset:2048
	ds_read_b128 v[148:151], v148 offset:3072
	ds_read_b128 v[152:155], v164
	ds_read_b128 v[156:159], v164 offset:1024
	ds_read_b128 v[160:163], v164 offset:2048
	ds_read_b128 v[172:175], v164 offset:3072
	v_lshl_add_u64 v[164:165], s[6:7], 0, v[134:135]
	s_add_i32 m0, s2, 0xc000
	ds_read_b128 v[176:179], v231
	ds_read_b128 v[180:183], v231 offset:1024
	ds_read_b128 v[184:187], v231 offset:2048
	ds_read_b128 v[188:191], v231 offset:3072
	ds_read_b128 v[192:195], v231 offset:4096
	ds_read_b128 v[196:199], v231 offset:5120
	ds_read_b128 v[200:203], v231 offset:6144
	ds_read_b128 v[204:207], v231 offset:7168
	global_load_lds_dwordx4 v[164:165], off
	v_lshl_add_u64 v[164:165], s[6:7], 0, v[132:133]
	s_add_i32 m0, s2, 0xe000
	s_nop 0
	global_load_lds_dwordx4 v[164:165], off
	s_waitcnt vmcnt(8)
	s_waitcnt lgkmcnt(0)
	s_barrier
; #define PG8_STAGE(bufoff, gbase, voff) do { _Pragma("unroll") for (int _i = 0; _i < 2; ++_i) \
;         __builtin_amdgcn_global_load_lds((const unsigned*)((const char*)(gbase) + (voff)[_i]), (PG8_LAS unsigned*)(lds + (bufoff) + ldsw + _i * 8192), 16, 0, 0); } while (0)
; #define PG8_LDA(dst, b, h) do { _Pragma("unroll") for (int m = 0; m < 4; ++m) _Pragma("unroll") for (int k = 0; k < 2; ++k) dst[m][k] = *(const PG8_LAS bf16x8*)(lds + PG8_SA(b, h) + aoff + m * 2048 + k * 1024); } while (0)
; #define PG8_LDB(dst, b, h) do { _Pragma("unroll") for (int n = 0; n < 2; ++n) _Pragma("unroll") for (int k = 0; k < 2; ++k) dst[n][k] = *(const PG8_LAS bf16x8*)(lds + PG8_SB(b, h) + boff + n * 2048 + k * 1024); } while (0)
; #define PG8_MMA(ai, bj, At, Bt) do { __builtin_amdgcn_s_setprio(1); _Pragma("unroll") for (int m = 0; m < 4; ++m) _Pragma("unroll") for (int n = 0; n < 2; ++n) _Pragma("unroll") for (int k = 0; k < 2; ++k) \
;         acc[ai][bj][m][n] = __builtin_amdgcn_mfma_f32_16x16x32_bf16(Bt[n][k], At[m][k], acc[ai][bj][m][n], 0, 0, 0); __builtin_amdgcn_s_setprio(0); } while (0)
; #define PG8_WAIT_V(n) asm volatile("s_waitcnt vmcnt(" #n ")" ::: "memory")
; #define PG8_WAIT_L(n) asm volatile("s_waitcnt lgkmcnt(" #n ")" ::: "memory")
; #define PG8_BAR __builtin_amdgcn_s_barrier()
; #define PG8_SCHED __builtin_amdgcn_sched_barrier(0)
;     ...
;             PG8_WAIT_V(8); PG8_WAIT_L(0); PG8_BAR; PG8_MMA(1, 0, At, B0); PG8_MMA(1, 1, At, B1); PG8_BAR; PG8_SCHED;
;             PG8_LDB(B0, 1, 0); PG8_LDB(B1, 1, 1); PG8_SCHED; PG8_LDA(At, 1, 0); PG8_STAGE(PG8_SA(0, 1), a2 + hstepA, voffA);
;             PG8_WAIT_V(8); PG8_WAIT_L(0); PG8_BAR; PG8_MMA(0, 0, At, B0); PG8_MMA(0, 1, At, B1); PG8_BAR; PG8_SCHED;
	s_waitcnt lgkmcnt(0)
	v_mfma_f32_16x16x32_bf16 v[126:129], v[136:139], v[176:179], v[126:129]
	v_mfma_f32_16x16x32_bf16 v[122:125], v[144:147], v[176:179], v[122:125]
	v_mfma_f32_16x16x32_bf16 v[110:113], v[136:139], v[184:187], v[110:113]
	v_mfma_f32_16x16x32_bf16 v[106:109], v[144:147], v[184:187], v[106:109]
	v_mfma_f32_16x16x32_bf16 v[94:97], v[136:139], v[192:195], v[94:97]
	v_mfma_f32_16x16x32_bf16 v[90:93], v[144:147], v[192:195], v[90:93]
	v_mfma_f32_16x16x32_bf16 v[78:81], v[136:139], v[200:203], v[78:81]
	v_mfma_f32_16x16x32_bf16 v[74:77], v[144:147], v[200:203], v[74:77]
	v_mfma_f32_16x16x32_bf16 v[126:129], v[140:143], v[180:183], v[126:129]
	v_mfma_f32_16x16x32_bf16 v[122:125], v[148:151], v[180:183], v[122:125]
	v_mfma_f32_16x16x32_bf16 v[110:113], v[140:143], v[188:191], v[110:113]
	v_mfma_f32_16x16x32_bf16 v[106:109], v[148:151], v[188:191], v[106:109]
	v_mfma_f32_16x16x32_bf16 v[94:97], v[140:143], v[196:199], v[94:97]
	v_mfma_f32_16x16x32_bf16 v[90:93], v[148:151], v[196:199], v[90:93]
	v_mfma_f32_16x16x32_bf16 v[78:81], v[140:143], v[204:207], v[78:81]
	v_mfma_f32_16x16x32_bf16 v[74:77], v[148:151], v[204:207], v[74:77]
	v_mfma_f32_16x16x32_bf16 v[118:121], v[152:155], v[176:179], v[118:121]
	v_mfma_f32_16x16x32_bf16 v[114:117], v[160:163], v[176:179], v[114:117]
	v_mfma_f32_16x16x32_bf16 v[102:105], v[152:155], v[184:187], v[102:105]
	v_mfma_f32_16x16x32_bf16 v[98:101], v[160:163], v[184:187], v[98:101]
	v_mfma_f32_16x16x32_bf16 v[86:89], v[152:155], v[192:195], v[86:89]
	v_mfma_f32_16x16x32_bf16 v[82:85], v[160:163], v[192:195], v[82:85]
	v_mfma_f32_16x16x32_bf16 v[70:73], v[152:155], v[200:203], v[70:73]
	v_mfma_f32_16x16x32_bf16 v[66:69], v[160:163], v[200:203], v[66:69]
	v_mfma_f32_16x16x32_bf16 v[118:121], v[156:159], v[180:183], v[118:121]
	v_mfma_f32_16x16x32_bf16 v[114:117], v[172:175], v[180:183], v[114:117]
	v_mfma_f32_16x16x32_bf16 v[102:105], v[156:159], v[188:191], v[102:105]
	v_mfma_f32_16x16x32_bf16 v[98:101], v[172:175], v[188:191], v[98:101]
	v_mfma_f32_16x16x32_bf16 v[86:89], v[156:159], v[196:199], v[86:89]
	v_mfma_f32_16x16x32_bf16 v[82:85], v[172:175], v[196:199], v[82:85]
	v_mfma_f32_16x16x32_bf16 v[70:73], v[156:159], v[204:207], v[70:73]
	v_mfma_f32_16x16x32_bf16 v[66:69], v[172:175], v[204:207], v[66:69]
	s_barrier
	s_add_i32 s31, s31, s0
	v_lshl_add_u64 v[164:165], s[34:35], 0, v[166:167]
	s_mov_b32 m0, s31
	ds_read_b128 v[176:179], v231 offset:16384
	ds_read_b128 v[180:183], v231 offset:17408
	ds_read_b128 v[184:187], v231 offset:18432
	ds_read_b128 v[188:191], v231 offset:19456
	ds_read_b128 v[192:195], v231 offset:20480
	ds_read_b128 v[196:199], v231 offset:21504
	ds_read_b128 v[200:203], v231 offset:22528
	ds_read_b128 v[204:207], v231 offset:23552
	global_load_lds_dwordx4 v[164:165], off
	s_add_i32 m0, s31, 0x2000
	v_lshl_add_u64 v[168:169], s[34:35], 0, v[130:131]
	s_add_u32 s34, s34, s60
	s_addc_u32 s35, s35, s61
	s_add_i32 s27, s27, s0
	global_load_lds_dwordx4 v[168:169], off
	v_lshl_add_u64 v[170:171], s[34:35], 0, v[166:167]
	s_mov_b32 m0, s27
	v_lshl_add_u64 v[208:209], s[34:35], 0, v[130:131]
	global_load_lds_dwordx4 v[170:171], off
	s_add_i32 m0, s27, 0x2000
	v_lshl_add_u64 v[210:211], s[8:9], 0, v[246:247]
	global_load_lds_dwordx4 v[208:209], off
	s_mov_b32 m0, s2
	v_lshl_add_u64 v[212:213], s[8:9], 0, v[248:249]
	global_load_lds_dwordx4 v[210:211], off
	s_mov_b32 m0, s3
	s_nop 0
	global_load_lds_dwordx4 v[212:213], off
	s_waitcnt vmcnt(8)
	s_waitcnt lgkmcnt(0)
	s_barrier
	s_waitcnt lgkmcnt(0)
	v_mfma_f32_16x16x32_bf16 v[62:65], v[136:139], v[176:179], v[62:65]
	v_mfma_f32_16x16x32_bf16 v[58:61], v[144:147], v[176:179], v[58:61]
	v_mfma_f32_16x16x32_bf16 v[46:49], v[136:139], v[184:187], v[46:49]
	v_mfma_f32_16x16x32_bf16 v[42:45], v[144:147], v[184:187], v[42:45]
	v_mfma_f32_16x16x32_bf16 v[30:33], v[136:139], v[192:195], v[30:33]
	v_mfma_f32_16x16x32_bf16 v[26:29], v[144:147], v[192:195], v[26:29]
	v_mfma_f32_16x16x32_bf16 v[14:17], v[136:139], v[200:203], v[14:17]
	v_mfma_f32_16x16x32_bf16 v[10:13], v[144:147], v[200:203], v[10:13]
	v_mfma_f32_16x16x32_bf16 v[62:65], v[140:143], v[180:183], v[62:65]
	v_mfma_f32_16x16x32_bf16 v[58:61], v[148:151], v[180:183], v[58:61]
	v_mfma_f32_16x16x32_bf16 v[46:49], v[140:143], v[188:191], v[46:49]
	v_mfma_f32_16x16x32_bf16 v[42:45], v[148:151], v[188:191], v[42:45]
	v_mfma_f32_16x16x32_bf16 v[30:33], v[140:143], v[196:199], v[30:33]
	v_mfma_f32_16x16x32_bf16 v[26:29], v[148:151], v[196:199], v[26:29]
	v_mfma_f32_16x16x32_bf16 v[14:17], v[140:143], v[204:207], v[14:17]
	v_mfma_f32_16x16x32_bf16 v[10:13], v[148:151], v[204:207], v[10:13]
	v_mfma_f32_16x16x32_bf16 v[54:57], v[152:155], v[176:179], v[54:57]
	v_mfma_f32_16x16x32_bf16 v[50:53], v[160:163], v[176:179], v[50:53]
	v_mfma_f32_16x16x32_bf16 v[38:41], v[152:155], v[184:187], v[38:41]
	v_mfma_f32_16x16x32_bf16 v[34:37], v[160:163], v[184:187], v[34:37]
	v_mfma_f32_16x16x32_bf16 v[22:25], v[152:155], v[192:195], v[22:25]
	v_mfma_f32_16x16x32_bf16 v[18:21], v[160:163], v[192:195], v[18:21]
	v_mfma_f32_16x16x32_bf16 v[6:9], v[152:155], v[200:203], v[6:9]
	v_mfma_f32_16x16x32_bf16 v[2:5], v[160:163], v[200:203], v[2:5]
	v_mfma_f32_16x16x32_bf16 v[54:57], v[156:159], v[180:183], v[54:57]
	v_mfma_f32_16x16x32_bf16 v[50:53], v[172:175], v[180:183], v[50:53]
	v_mfma_f32_16x16x32_bf16 v[38:41], v[156:159], v[188:191], v[38:41]
	v_mfma_f32_16x16x32_bf16 v[34:37], v[172:175], v[188:191], v[34:37]
	v_mfma_f32_16x16x32_bf16 v[22:25], v[156:159], v[196:199], v[22:25]
	v_mfma_f32_16x16x32_bf16 v[18:21], v[172:175], v[196:199], v[18:21]
	v_mfma_f32_16x16x32_bf16 v[6:9], v[156:159], v[204:207], v[6:9]
	v_mfma_f32_16x16x32_bf16 v[2:5], v[172:175], v[204:207], v[2:5]
	s_barrier
; #define PG8_STAGE(bufoff, gbase, voff) do { _Pragma("unroll") for (int _i = 0; _i < 2; ++_i) \
;         __builtin_amdgcn_global_load_lds((const unsigned*)((const char*)(gbase) + (voff)[_i]), (PG8_LAS unsigned*)(lds + (bufoff) + ldsw + _i * 8192), 16, 0, 0); } while (0)
; #define PG8_LDA(dst, b, h) do { _Pragma("unroll") for (int m = 0; m < 4; ++m) _Pragma("unroll") for (int k = 0; k < 2; ++k) dst[m][k] = *(const PG8_LAS bf16x8*)(lds + PG8_SA(b, h) + aoff + m * 2048 + k * 1024); } while (0)
; #define PG8_MMA(ai, bj, At, Bt) do { __builtin_amdgcn_s_setprio(1); _Pragma("unroll") for (int m = 0; m < 4; ++m) _Pragma("unroll") for (int n = 0; n < 2; ++n) _Pragma("unroll") for (int k = 0; k < 2; ++k) \
;         acc[ai][bj][m][n] = __builtin_amdgcn_mfma_f32_16x16x32_bf16(Bt[n][k], At[m][k], acc[ai][bj][m][n], 0, 0, 0); __builtin_amdgcn_s_setprio(0); } while (0)
; #define PG8_WAIT_V(n) asm volatile("s_waitcnt vmcnt(" #n ")" ::: "memory")
; #define PG8_WAIT_L(n) asm volatile("s_waitcnt lgkmcnt(" #n ")" ::: "memory")
; #define PG8_BAR __builtin_amdgcn_s_barrier()
; #define PG8_SCHED __builtin_amdgcn_sched_barrier(0)
;     ...
;             PG8_LDA(At, 1, 1); PG8_STAGE(PG8_SB(1, 0), b3, voffB); PG8_STAGE(PG8_SB(1, 1), b3 + hstepB, voffB); PG8_STAGE(PG8_SA(1, 0), a3, voffA);
;             PG8_WAIT_V(8); PG8_WAIT_L(0); PG8_BAR; PG8_MMA(1, 0, At, B0); PG8_MMA(1, 1, At, B1); PG8_BAR; PG8_SCHED;
	s_add_i32 s27, 0, 0x18000
	s_add_i32 s31, 0, 0x1c000
	v_add_u32_e32 v148, s27, v229
	v_add_u32_e32 v172, s31, v229
	ds_read_b128 v[136:139], v148
	ds_read_b128 v[140:143], v148 offset:1024
	ds_read_b128 v[144:147], v148 offset:2048
	ds_read_b128 v[148:151], v148 offset:3072
	ds_read_b128 v[152:155], v172
	ds_read_b128 v[156:159], v172 offset:1024
	ds_read_b128 v[160:163], v172 offset:2048
	ds_read_b128 v[172:175], v172 offset:3072
	s_add_u32 s8, s8, s101
	s_addc_u32 s9, s9, 0
	s_mov_b32 m0, s14
	v_lshl_add_u64 v[214:215], s[8:9], 0, v[246:247]
	ds_read_b128 v[176:179], v231 offset:32768
	ds_read_b128 v[180:183], v231 offset:33792
	ds_read_b128 v[184:187], v231 offset:34816
	ds_read_b128 v[188:191], v231 offset:35840
	ds_read_b128 v[192:195], v231 offset:36864
	ds_read_b128 v[196:199], v231 offset:37888
	ds_read_b128 v[200:203], v231 offset:38912
	ds_read_b128 v[204:207], v231 offset:39936
	global_load_lds_dwordx4 v[214:215], off
	v_lshl_add_u64 v[214:215], s[8:9], 0, v[248:249]
	s_mov_b32 m0, s15
	s_nop 0
	global_load_lds_dwordx4 v[214:215], off
	s_waitcnt vmcnt(8)
	s_waitcnt lgkmcnt(0)
	s_barrier
	s_waitcnt lgkmcnt(0)
	v_mfma_f32_16x16x32_bf16 v[126:129], v[136:139], v[176:179], v[126:129]
	v_mfma_f32_16x16x32_bf16 v[122:125], v[144:147], v[176:179], v[122:125]
	v_mfma_f32_16x16x32_bf16 v[110:113], v[136:139], v[184:187], v[110:113]
	v_mfma_f32_16x16x32_bf16 v[106:109], v[144:147], v[184:187], v[106:109]
	v_mfma_f32_16x16x32_bf16 v[94:97], v[136:139], v[192:195], v[94:97]
	v_mfma_f32_16x16x32_bf16 v[90:93], v[144:147], v[192:195], v[90:93]
	v_mfma_f32_16x16x32_bf16 v[78:81], v[136:139], v[200:203], v[78:81]
	v_mfma_f32_16x16x32_bf16 v[74:77], v[144:147], v[200:203], v[74:77]
	v_mfma_f32_16x16x32_bf16 v[126:129], v[140:143], v[180:183], v[126:129]
	v_mfma_f32_16x16x32_bf16 v[122:125], v[148:151], v[180:183], v[122:125]
	v_mfma_f32_16x16x32_bf16 v[110:113], v[140:143], v[188:191], v[110:113]
	v_mfma_f32_16x16x32_bf16 v[106:109], v[148:151], v[188:191], v[106:109]
	v_mfma_f32_16x16x32_bf16 v[94:97], v[140:143], v[196:199], v[94:97]
	v_mfma_f32_16x16x32_bf16 v[90:93], v[148:151], v[196:199], v[90:93]
	v_mfma_f32_16x16x32_bf16 v[78:81], v[140:143], v[204:207], v[78:81]
	v_mfma_f32_16x16x32_bf16 v[74:77], v[148:151], v[204:207], v[74:77]
	v_mfma_f32_16x16x32_bf16 v[118:121], v[152:155], v[176:179], v[118:121]
	v_mfma_f32_16x16x32_bf16 v[114:117], v[160:163], v[176:179], v[114:117]
	v_mfma_f32_16x16x32_bf16 v[102:105], v[152:155], v[184:187], v[102:105]
	v_mfma_f32_16x16x32_bf16 v[98:101], v[160:163], v[184:187], v[98:101]
	v_mfma_f32_16x16x32_bf16 v[86:89], v[152:155], v[192:195], v[86:89]
	v_mfma_f32_16x16x32_bf16 v[82:85], v[160:163], v[192:195], v[82:85]
	v_mfma_f32_16x16x32_bf16 v[70:73], v[152:155], v[200:203], v[70:73]
	v_mfma_f32_16x16x32_bf16 v[66:69], v[160:163], v[200:203], v[66:69]
	v_mfma_f32_16x16x32_bf16 v[118:121], v[156:159], v[180:183], v[118:121]
	v_mfma_f32_16x16x32_bf16 v[114:117], v[172:175], v[180:183], v[114:117]
	v_mfma_f32_16x16x32_bf16 v[102:105], v[156:159], v[188:191], v[102:105]
	v_mfma_f32_16x16x32_bf16 v[98:101], v[172:175], v[188:191], v[98:101]
	v_mfma_f32_16x16x32_bf16 v[86:89], v[156:159], v[196:199], v[86:89]
	v_mfma_f32_16x16x32_bf16 v[82:85], v[172:175], v[196:199], v[82:85]
	v_mfma_f32_16x16x32_bf16 v[70:73], v[156:159], v[204:207], v[70:73]
	v_mfma_f32_16x16x32_bf16 v[66:69], v[172:175], v[204:207], v[66:69]
	s_barrier
	s_add_i32 s8, s27, s0
	v_lshl_add_u64 v[164:165], v[164:165], 0, s[62:63]
	s_mov_b32 m0, s8
	ds_read_b128 v[176:179], v231 offset:49152
	ds_read_b128 v[180:183], v231 offset:50176
	ds_read_b128 v[184:187], v231 offset:51200
	ds_read_b128 v[188:191], v231 offset:52224
	ds_read_b128 v[192:195], v231 offset:53248
	ds_read_b128 v[196:199], v231 offset:54272
	ds_read_b128 v[200:203], v231 offset:55296
	ds_read_b128 v[204:207], v231 offset:56320
	global_load_lds_dwordx4 v[164:165], off
	v_lshl_add_u64 v[164:165], v[168:169], 0, s[62:63]
	s_add_i32 m0, s8, 0x2000
	s_add_i32 s8, s31, s0
	global_load_lds_dwordx4 v[164:165], off
	v_lshl_add_u64 v[164:165], v[170:171], 0, s[62:63]
	s_mov_b32 m0, s8
	s_nop 0
	global_load_lds_dwordx4 v[164:165], off
	v_lshl_add_u64 v[164:165], v[208:209], 0, s[62:63]
	s_add_i32 m0, s8, 0x2000
	s_nop 0
	global_load_lds_dwordx4 v[164:165], off
	v_lshl_add_u64 v[164:165], v[210:211], 0, v[244:245]
	s_mov_b32 m0, s17
	s_nop 0
	global_load_lds_dwordx4 v[164:165], off
	v_lshl_add_u64 v[164:165], v[212:213], 0, v[244:245]
	s_mov_b32 m0, s18
	s_nop 0
	global_load_lds_dwordx4 v[164:165], off
	s_waitcnt vmcnt(8)
	s_waitcnt lgkmcnt(0)
	s_barrier
	s_waitcnt lgkmcnt(0)
	v_mfma_f32_16x16x32_bf16 v[62:65], v[136:139], v[176:179], v[62:65]
	v_mfma_f32_16x16x32_bf16 v[58:61], v[144:147], v[176:179], v[58:61]
	v_mfma_f32_16x16x32_bf16 v[46:49], v[136:139], v[184:187], v[46:49]
	v_mfma_f32_16x16x32_bf16 v[42:45], v[144:147], v[184:187], v[42:45]
	v_mfma_f32_16x16x32_bf16 v[30:33], v[136:139], v[192:195], v[30:33]
	v_mfma_f32_16x16x32_bf16 v[26:29], v[144:147], v[192:195], v[26:29]
	v_mfma_f32_16x16x32_bf16 v[14:17], v[136:139], v[200:203], v[14:17]
	v_mfma_f32_16x16x32_bf16 v[10:13], v[144:147], v[200:203], v[10:13]
	v_mfma_f32_16x16x32_bf16 v[62:65], v[140:143], v[180:183], v[62:65]
	v_mfma_f32_16x16x32_bf16 v[58:61], v[148:151], v[180:183], v[58:61]
	v_mfma_f32_16x16x32_bf16 v[46:49], v[140:143], v[188:191], v[46:49]
	v_mfma_f32_16x16x32_bf16 v[42:45], v[148:151], v[188:191], v[42:45]
	v_mfma_f32_16x16x32_bf16 v[30:33], v[140:143], v[196:199], v[30:33]
	v_mfma_f32_16x16x32_bf16 v[26:29], v[148:151], v[196:199], v[26:29]
	v_mfma_f32_16x16x32_bf16 v[14:17], v[140:143], v[204:207], v[14:17]
	v_mfma_f32_16x16x32_bf16 v[10:13], v[148:151], v[204:207], v[10:13]
	v_mfma_f32_16x16x32_bf16 v[54:57], v[152:155], v[176:179], v[54:57]
	v_mfma_f32_16x16x32_bf16 v[50:53], v[160:163], v[176:179], v[50:53]
	v_mfma_f32_16x16x32_bf16 v[38:41], v[152:155], v[184:187], v[38:41]
	v_mfma_f32_16x16x32_bf16 v[34:37], v[160:163], v[184:187], v[34:37]
	v_mfma_f32_16x16x32_bf16 v[22:25], v[152:155], v[192:195], v[22:25]
	v_mfma_f32_16x16x32_bf16 v[18:21], v[160:163], v[192:195], v[18:21]
	v_mfma_f32_16x16x32_bf16 v[6:9], v[152:155], v[200:203], v[6:9]
	v_mfma_f32_16x16x32_bf16 v[2:5], v[160:163], v[200:203], v[2:5]
	v_mfma_f32_16x16x32_bf16 v[54:57], v[156:159], v[180:183], v[54:57]
	v_mfma_f32_16x16x32_bf16 v[50:53], v[172:175], v[180:183], v[50:53]
	v_mfma_f32_16x16x32_bf16 v[38:41], v[156:159], v[188:191], v[38:41]
	v_mfma_f32_16x16x32_bf16 v[34:37], v[172:175], v[188:191], v[34:37]
	v_mfma_f32_16x16x32_bf16 v[22:25], v[156:159], v[196:199], v[22:25]
	v_mfma_f32_16x16x32_bf16 v[18:21], v[172:175], v[196:199], v[18:21]
	v_mfma_f32_16x16x32_bf16 v[6:9], v[156:159], v[204:207], v[6:9]
	v_mfma_f32_16x16x32_bf16 v[2:5], v[172:175], v[204:207], v[2:5]
	s_barrier
	s_add_u32 s10, s10, 0x100
	s_addc_u32 s11, s11, 0
	v_readlane_b32 s31, v255, 41
	s_add_u32 s6, s6, s31
	s_addc_u32 s7, s7, 0
	s_cmp_ge_i32 s25, s13
	s_mov_b32 s8, s25
	s_cbranch_scc0 .LBB0_520
